# de-serialised LDS/global load chains: SWA K/V staging loads issued together, DeltaNet triangular inverse + rhs build with reads in flight, HGRN diagonal pairs with batched b128 reads
# speedup vs baseline: 1.0376x; 1.0376x over previous
; __device__ __forceinline__ float bf2f(bfu h) { return __uint_as_float(((unsigned)h) << 16); }
; #define SHX(v, m) shx_((v), (m), lane)
; __device__ void hg_pre_item(const Params& p, int L, int idx) {
;     ...
;   for (int rd = 0; rd < 9; ++rd) {
;     const int pi = (rd * NTHR + tid) >> 3, part = tid & 7;
;     const bool act = pi < 544;
;     const int pj = act ? pi : 0;
;     const int blk = pj / 136, tri = pj - blk * 136;
;     int t = (int)((__builtin_amdgcn_sqrtf((float)(8 * tri + 1)) - 1.0f) * 0.5f);
;     if ((t + 1) * (t + 2) / 2 <= tri) ++t;
;     if (t * (t + 1) / 2 > tri) --t;
;     const int s = tri - t * (t + 1) / 2;
;     const int T = blk * 16 + t, S = blk * 16 + s;
;     float acc = 0.f;
;     _Pragma("unroll") for (int e = 0; e < 16; ++e) {
;       const int d = part * 16 + e;
;       acc += bf2f(qb[T * 136 + d]) * bf2f(kb[S * 136 + d]) * __builtin_amdgcn_exp2f(bs[T * 132 + d] - bs[S * 132 + d]);
;     }
;     acc += SHX(acc, 1); acc += SHX(acc, 2); acc += SHX(acc, 4);
;     if (part == 0 && act) at[T * 72 + S] = f2bf(acc);
;   }
.LBB0_62:
	v_add_u32_e32 v2, s12, v18
	v_ashrrev_i32_e32 v2, 3, v2
	s_movk_i32 s0, 0x220
	v_cmp_gt_i32_e64 s[38:39], s0, v2
	s_mov_b32 s0, 0x78787879
	s_movk_i32 s2, 0x210
	v_cndmask_b32_e64 v2, 0, v2, s[38:39]
	s_waitcnt lgkmcnt(0)
	v_mul_hi_i32 v3, v2, s0
	v_lshrrev_b32_e32 v4, 31, v3
	v_ashrrev_i32_e32 v3, 6, v3
	v_add_u32_e32 v3, v3, v4
	s_movk_i32 s0, 0xff78
	v_mad_i32_i24 v6, v3, s0, v2
	v_lshl_or_b32 v2, v6, 3, 1
	v_cvt_f32_i32_e32 v2, v2
	v_sqrt_f32_e32 v2, v2
	s_nop 0
	v_add_f32_e32 v2, -1.0, v2
	v_mul_f32_e32 v2, 0.5, v2
	v_cvt_i32_f32_e32 v2, v2
	v_add_u32_e32 v4, 1, v2
	v_add_u32_e32 v5, 2, v2
	v_mul_lo_u32 v5, v4, v5
	v_lshrrev_b32_e32 v7, 31, v5
	v_add_u32_e32 v5, v5, v7
	v_ashrrev_i32_e32 v5, 1, v5
	v_cmp_gt_i32_e64 s[0:1], v5, v6
	s_nop 1
	v_cndmask_b32_e64 v2, v4, v2, s[0:1]
	v_mad_u64_u32 v[4:5], s[0:1], v2, v2, v[2:3]
	v_lshrrev_b32_e32 v5, 31, v4
	v_add_u32_e32 v4, v4, v5
	v_ashrrev_i32_e32 v4, 1, v4
	v_cmp_gt_i32_e64 s[0:1], v4, v6
	s_nop 1
	v_subbrev_co_u32_e64 v2, s[0:1], 0, v2, s[0:1]
	v_mad_u64_u32 v[4:5], s[0:1], v2, v2, v[2:3]
	v_lshrrev_b32_e32 v5, 31, v4
	v_add_u32_e32 v4, v4, v5
	v_lshlrev_b32_e32 v3, 4, v3
	v_ashrrev_i32_e32 v4, 1, v4
	v_add_u32_e32 v33, v2, v3
	v_add_u32_e32 v2, v6, v3
	v_sub_u32_e32 v34, v2, v4
	v_mad_u64_u32 v[2:3], s[0:1], v33, s88, v[0:1]
	v_mad_u64_u32 v[6:7], s[0:1], v34, s88, v[0:1]
	v_mad_u64_u32 v[28:29], s[0:1], v33, s2, v[24:25]
	v_mad_u64_u32 v[26:27], s[0:1], v34, s2, v[24:25]
	s_and_b64 s[2:3], vcc, s[38:39]
	ds_read_b128 v[112:115], v2 offset:33792
	ds_read_b128 v[116:119], v2 offset:33808
	ds_read_b128 v[120:123], v6 offset:51200
	ds_read_b128 v[124:127], v6 offset:51216
	ds_read_b128 v[128:131], v28
	ds_read_b128 v[132:135], v28 offset:16
	ds_read_b128 v[136:139], v28 offset:32
	ds_read_b128 v[140:143], v28 offset:48
	ds_read_b128 v[144:147], v26
	ds_read_b128 v[148:151], v26 offset:16
	ds_read_b128 v[152:155], v26 offset:32
	ds_read_b128 v[156:159], v26 offset:48
	s_waitcnt lgkmcnt(0)
	v_lshlrev_b32_e32 v160, 16, v112
	v_lshlrev_b32_e32 v161, 16, v120
	v_and_b32_e32 v162, 0xffff0000, v112
	v_and_b32_e32 v163, 0xffff0000, v120
	v_mul_f32_e32 v160, v160, v161
	v_mul_f32_e32 v162, v162, v163
	v_sub_f32_e32 v161, v128, v144
	v_sub_f32_e32 v163, v129, v145
	v_exp_f32_e32 v161, v161
	v_exp_f32_e32 v163, v163
	v_mul_f32_e32 v27, v160, v161
	v_fmac_f32_e32 v27, v162, v163
	v_lshlrev_b32_e32 v160, 16, v113
	v_lshlrev_b32_e32 v161, 16, v121
	v_and_b32_e32 v162, 0xffff0000, v113
	v_and_b32_e32 v163, 0xffff0000, v121
	v_mul_f32_e32 v160, v160, v161
	v_mul_f32_e32 v162, v162, v163
	v_sub_f32_e32 v161, v130, v146
	v_sub_f32_e32 v163, v131, v147
	v_exp_f32_e32 v161, v161
	v_exp_f32_e32 v163, v163
	v_fmac_f32_e32 v27, v160, v161
	v_fmac_f32_e32 v27, v162, v163
	v_lshlrev_b32_e32 v160, 16, v114
	v_lshlrev_b32_e32 v161, 16, v122
	v_and_b32_e32 v162, 0xffff0000, v114
	v_and_b32_e32 v163, 0xffff0000, v122
	v_mul_f32_e32 v160, v160, v161
	v_mul_f32_e32 v162, v162, v163
	v_sub_f32_e32 v161, v132, v148
	v_sub_f32_e32 v163, v133, v149
	v_exp_f32_e32 v161, v161
	v_exp_f32_e32 v163, v163
	v_fmac_f32_e32 v27, v160, v161
	v_fmac_f32_e32 v27, v162, v163
	v_lshlrev_b32_e32 v160, 16, v115
	v_lshlrev_b32_e32 v161, 16, v123
	v_and_b32_e32 v162, 0xffff0000, v115
	v_and_b32_e32 v163, 0xffff0000, v123
	v_mul_f32_e32 v160, v160, v161
	v_mul_f32_e32 v162, v162, v163
	v_sub_f32_e32 v161, v134, v150
	v_sub_f32_e32 v163, v135, v151
	v_exp_f32_e32 v161, v161
	v_exp_f32_e32 v163, v163
	v_fmac_f32_e32 v27, v160, v161
	v_fmac_f32_e32 v27, v162, v163
	v_lshlrev_b32_e32 v160, 16, v116
	v_lshlrev_b32_e32 v161, 16, v124
	v_and_b32_e32 v162, 0xffff0000, v116
	v_and_b32_e32 v163, 0xffff0000, v124
	v_mul_f32_e32 v160, v160, v161
	v_mul_f32_e32 v162, v162, v163
	v_sub_f32_e32 v161, v136, v152
	v_sub_f32_e32 v163, v137, v153
	v_exp_f32_e32 v161, v161
	v_exp_f32_e32 v163, v163
	v_fmac_f32_e32 v27, v160, v161
	v_fmac_f32_e32 v27, v162, v163
	v_lshlrev_b32_e32 v160, 16, v117
	v_lshlrev_b32_e32 v161, 16, v125
	v_and_b32_e32 v162, 0xffff0000, v117
	v_and_b32_e32 v163, 0xffff0000, v125
	v_mul_f32_e32 v160, v160, v161
	v_mul_f32_e32 v162, v162, v163
	v_sub_f32_e32 v161, v138, v154
	v_sub_f32_e32 v163, v139, v155
	v_exp_f32_e32 v161, v161
	v_exp_f32_e32 v163, v163
	v_fmac_f32_e32 v27, v160, v161
	v_fmac_f32_e32 v27, v162, v163
	v_lshlrev_b32_e32 v160, 16, v118
	v_lshlrev_b32_e32 v161, 16, v126
	v_and_b32_e32 v162, 0xffff0000, v118
	v_and_b32_e32 v163, 0xffff0000, v126
	v_mul_f32_e32 v160, v160, v161
	v_mul_f32_e32 v162, v162, v163
	v_sub_f32_e32 v161, v140, v156
	v_sub_f32_e32 v163, v141, v157
	v_exp_f32_e32 v161, v161
	v_exp_f32_e32 v163, v163
	v_fmac_f32_e32 v27, v160, v161
	v_fmac_f32_e32 v27, v162, v163
	v_lshlrev_b32_e32 v160, 16, v119
	v_lshlrev_b32_e32 v161, 16, v127
	v_and_b32_e32 v162, 0xffff0000, v119
	v_and_b32_e32 v163, 0xffff0000, v127
	v_mul_f32_e32 v160, v160, v161
	v_mul_f32_e32 v162, v162, v163
	v_sub_f32_e32 v161, v142, v158
	v_sub_f32_e32 v163, v143, v159
	v_exp_f32_e32 v161, v161
	v_exp_f32_e32 v163, v163
	v_fmac_f32_e32 v27, v160, v161
	v_fmac_f32_e32 v27, v162, v163
	ds_bpermute_b32 v2, v30, v27
	s_waitcnt lgkmcnt(0)
	v_add_f32_e32 v2, v27, v2
	ds_bpermute_b32 v3, v31, v2
	s_waitcnt lgkmcnt(0)
	v_add_f32_e32 v2, v2, v3
	ds_bpermute_b32 v3, v32, v2
	s_and_saveexec_b64 s[0:1], s[2:3]
	s_cbranch_execz .LBB0_61
	s_waitcnt lgkmcnt(0)
	v_add_f32_e32 v2, v2, v3
	v_bfe_u32 v3, v2, 16, 1
	v_add3_u32 v2, v2, v3, s72
	v_mul_lo_u32 v3, v33, s70
	v_lshlrev_b32_e32 v4, 1, v34
	v_add3_u32 v3, v25, v3, v4
	ds_write_b16_d16_hi v3, v2
	s_branch .LBB0_61

; __device__ void swa_item(const Params& p, int item) {
;     ...
;   __syncthreads();
;   _Pragma("unroll") for (int i = 0; i < 4; ++i) {
;     int co = tid + 512 * i; int c8 = co & 15, kp = co >> 4;
;     int j0 = qb * 128 - 128 + 2 * kp;
;     const int j0c = (j0 >= 0) ? j0 : 0;
;     bf16x8 v0 = *(const bf16x8*)(buf + (rowb + (long)j0c * dil + r) * 4608 + vcol + c8 * 8);
;     bf16x8 v1 = *(const bf16x8*)(buf + (rowb + (long)(j0c + 1) * dil + r) * 4608 + vcol + c8 * 8);
;     if (j0 < 0) { v0 = (bf16x8){0, 0, 0, 0, 0, 0, 0, 0}; v1 = v0; }
;     const int chs = ((kp >> 2) ^ c8) * 8 + ((2 * kp) & 7);
;     _Pragma("unroll") for (int e = 0; e < 8; ++e)
;       *(unsigned*)(Vt + (c8 * 8 + e) * 280 + chs) = (unsigned)(bfu)v0[e] | ((unsigned)(bfu)v1[e] << 16);
;   }
;   _Pragma("unroll") for (int i = 0; i < 8; ++i) {
;     int co = tid + 512 * i; int c8 = co & 15, kj = co >> 4;
;     int j = qb * 128 - 128 + kj; j = (j >= 0) ? j : 0;
;     *(bf16x8*)(Ks + kj * 136 + c8 * 8) = *(const bf16x8*)(buf + (rowb + (long)j * dil + r) * 4608 + kcol + c8 * 8);
;   }
.LBB0_102:
	s_cmpk_gt_i32 s21, 0xbff
	s_cbranch_scc1 .LBB0_113
	s_ashr_i32 s88, s21, 10
	s_bfe_u32 s23, s21, 0x20005
	s_and_b32 s0, s21, 31
	s_cmp_eq_u32 s88, 1
	s_cselect_b32 s1, 2, 4
	s_cmpk_gt_u32 s21, 0x3ff
	s_cselect_b32 s22, s1, 0
	s_lshr_b32 s1, 32, s22
	s_sub_i32 s2, 5, s22
	s_add_i32 s1, s1, -1
	s_lshr_b32 s2, s0, s2
	s_and_b32 s34, s1, s0
	s_lshl_b32 s0, s21, 5
	s_and_b32 s1, s0, 0x7000
	s_lshl_b32 s0, s88, 9
	s_lshl_b32 s3, s23, 7
	s_or_b32 s0, s3, s0
	v_readlane_b32 s18, v254, 13
	s_lshl_b32 s35, s34, 7
	s_or_b32 s18, s2, s1
	s_ashr_i32 s1, s0, 31
	v_mbcnt_lo_u32_b32 v0, -1, 0
	v_mbcnt_hi_u32_b32 v0, -1, v0
	s_add_i32 s12, s35, 0xffffff80
	v_or_b32_e32 v50, s33, v0
	s_lshl_b64 s[2:3], s[0:1], 1
	s_add_u32 s52, s16, s2
	v_and_b32_e32 v55, 15, v50
	s_addc_u32 s53, s17, s3
	v_lshlrev_b32_e32 v0, 4, v55
	v_ashrrev_i32_e32 v13, 3, v50
	s_waitcnt lgkmcnt(0)
	v_lshl_add_u64 v[2:3], s[52:53], 0, v[0:1]
	v_and_b32_e32 v0, -2, v13
	v_add_u32_e32 v14, s12, v0
	s_mov_b64 s[2:3], 0x1800
	v_max_i32_e32 v0, 0, v14
	v_lshl_add_u64 v[10:11], v[2:3], 0, s[2:3]
	v_lshlrev_b64 v[2:3], s22, v[0:1]
	v_or_b32_e32 v0, 1, v0
	v_readlane_b32 s19, v254, 14
	v_lshlrev_b64 v[6:7], s22, v[0:1]
	s_nop 0
	v_lshl_add_u64 v[2:3], v[2:3], 0, s[18:19]
	v_lshl_add_u64 v[6:7], v[6:7], 0, s[18:19]
	v_mad_u64_u32 v[4:5], s[2:3], v2, s89, v[10:11]
	v_mad_u64_u32 v[8:9], s[2:3], v6, s89, v[10:11]
	v_mad_u32_u24 v5, v3, s89, v5
	v_mad_u32_u24 v9, v7, s89, v9
	s_barrier
	v_lshlrev_b32_e32 v140, 4, v55
	v_mov_b32_e32 v141, 0
	v_lshl_add_u64 v[140:141], s[52:53], 0, v[140:141]
	s_mov_b64 s[2:3], 0x1800
	v_lshl_add_u64 v[142:143], v[140:141], 0, s[2:3]
	v_lshrrev_b32_e32 v144, 4, v50
	v_lshl_add_u32 v145, v144, 1, s12
	v_max_i32_e32 v146, 0, v145
	v_lshlrev_b32_e32 v147, s22, v146
	v_add_u32_e32 v147, s18, v147
	v_mad_u64_u32 v[148:149], vcc, v147, s89, v[142:143]
	global_load_dwordx4 v[76:79], v[148:149], off
	v_or_b32_e32 v146, 1, v146
	v_lshlrev_b32_e32 v147, s22, v146
	v_add_u32_e32 v147, s18, v147
	v_mad_u64_u32 v[148:149], vcc, v147, s89, v[142:143]
	global_load_dwordx4 v[80:83], v[148:149], off
	v_add_u32_e32 v146, 64, v145
	v_max_i32_e32 v146, 0, v146
	v_lshlrev_b32_e32 v147, s22, v146
	v_add_u32_e32 v147, s18, v147
	v_mad_u64_u32 v[148:149], vcc, v147, s89, v[142:143]
	global_load_dwordx4 v[84:87], v[148:149], off
	v_or_b32_e32 v146, 1, v146
	v_lshlrev_b32_e32 v147, s22, v146
	v_add_u32_e32 v147, s18, v147
	v_mad_u64_u32 v[148:149], vcc, v147, s89, v[142:143]
	global_load_dwordx4 v[88:91], v[148:149], off
	v_add_u32_e32 v146, 128, v145
	v_max_i32_e32 v146, 0, v146
	v_lshlrev_b32_e32 v147, s22, v146
	v_add_u32_e32 v147, s18, v147
	v_mad_u64_u32 v[148:149], vcc, v147, s89, v[142:143]
	global_load_dwordx4 v[92:95], v[148:149], off
	v_or_b32_e32 v146, 1, v146
	v_lshlrev_b32_e32 v147, s22, v146
	v_add_u32_e32 v147, s18, v147
	v_mad_u64_u32 v[148:149], vcc, v147, s89, v[142:143]
	global_load_dwordx4 v[96:99], v[148:149], off
	v_add_u32_e32 v146, 192, v145
	v_max_i32_e32 v146, 0, v146
	v_lshlrev_b32_e32 v147, s22, v146
	v_add_u32_e32 v147, s18, v147
	v_mad_u64_u32 v[148:149], vcc, v147, s89, v[142:143]
	global_load_dwordx4 v[100:103], v[148:149], off
	v_or_b32_e32 v146, 1, v146
	v_lshlrev_b32_e32 v147, s22, v146
	v_add_u32_e32 v147, s18, v147
	v_mad_u64_u32 v[148:149], vcc, v147, s89, v[142:143]
	global_load_dwordx4 v[104:107], v[148:149], off
	v_add_u32_e32 v145, s12, v144
	v_max_i32_e32 v146, 0, v145
	v_lshlrev_b32_e32 v147, s22, v146
	v_add_u32_e32 v147, s18, v147
	v_mad_u64_u32 v[148:149], vcc, v147, s89, v[140:141]
	global_load_dwordx4 v[108:111], v[148:149], off offset:3072
	v_add_u32_e32 v146, 32, v145
	v_max_i32_e32 v146, 0, v146
	v_lshlrev_b32_e32 v147, s22, v146
	v_add_u32_e32 v147, s18, v147
	v_mad_u64_u32 v[148:149], vcc, v147, s89, v[140:141]
	global_load_dwordx4 v[112:115], v[148:149], off offset:3072
	v_add_u32_e32 v146, 64, v145
	v_max_i32_e32 v146, 0, v146
	v_lshlrev_b32_e32 v147, s22, v146
	v_add_u32_e32 v147, s18, v147
	v_mad_u64_u32 v[148:149], vcc, v147, s89, v[140:141]
	global_load_dwordx4 v[116:119], v[148:149], off offset:3072
	v_add_u32_e32 v146, 96, v145
	v_max_i32_e32 v146, 0, v146
	v_lshlrev_b32_e32 v147, s22, v146
	v_add_u32_e32 v147, s18, v147
	v_mad_u64_u32 v[148:149], vcc, v147, s89, v[140:141]
	global_load_dwordx4 v[120:123], v[148:149], off offset:3072
	v_add_u32_e32 v146, 128, v145
	v_max_i32_e32 v146, 0, v146
	v_lshlrev_b32_e32 v147, s22, v146
	v_add_u32_e32 v147, s18, v147
	v_mad_u64_u32 v[148:149], vcc, v147, s89, v[140:141]
	global_load_dwordx4 v[124:127], v[148:149], off offset:3072
	v_add_u32_e32 v146, 160, v145
	v_max_i32_e32 v146, 0, v146
	v_lshlrev_b32_e32 v147, s22, v146
	v_add_u32_e32 v147, s18, v147
	v_mad_u64_u32 v[148:149], vcc, v147, s89, v[140:141]
	global_load_dwordx4 v[128:131], v[148:149], off offset:3072
	v_add_u32_e32 v146, 192, v145
	v_max_i32_e32 v146, 0, v146
	v_lshlrev_b32_e32 v147, s22, v146
	v_add_u32_e32 v147, s18, v147
	v_mad_u64_u32 v[148:149], vcc, v147, s89, v[140:141]
	global_load_dwordx4 v[132:135], v[148:149], off offset:3072
	v_add_u32_e32 v146, 224, v145
	v_max_i32_e32 v146, 0, v146
	v_lshlrev_b32_e32 v147, s22, v146
	v_add_u32_e32 v147, s18, v147
	v_mad_u64_u32 v[148:149], vcc, v147, s89, v[140:141]
	global_load_dwordx4 v[136:139], v[148:149], off offset:3072
	s_waitcnt vmcnt(14)
; __device__ void swa_item(const Params& p, int item) {
;     ...
;   _Pragma("unroll") for (int i = 0; i < 4; ++i) {
;     int co = tid + 512 * i; int c8 = co & 15, kp = co >> 4;
;     int j0 = qb * 128 - 128 + 2 * kp;
;     const int j0c = (j0 >= 0) ? j0 : 0;
;     bf16x8 v0 = *(const bf16x8*)(buf + (rowb + (long)j0c * dil + r) * 4608 + vcol + c8 * 8);
;     bf16x8 v1 = *(const bf16x8*)(buf + (rowb + (long)(j0c + 1) * dil + r) * 4608 + vcol + c8 * 8);
;     if (j0 < 0) { v0 = (bf16x8){0, 0, 0, 0, 0, 0, 0, 0}; v1 = v0; }
;     const int chs = ((kp >> 2) ^ c8) * 8 + ((2 * kp) & 7);
;     _Pragma("unroll") for (int e = 0; e < 8; ++e)
;       *(unsigned*)(Vt + (c8 * 8 + e) * 280 + chs) = (unsigned)(bfu)v0[e] | ((unsigned)(bfu)v1[e] << 16);
;   }
	v_mov_b64_e32 v[2:3], v[76:77]
	v_mov_b64_e32 v[4:5], v[78:79]
	v_ashrrev_i32_e32 v12, 6, v50
	v_mov_b64_e32 v[6:7], v[80:81]
	v_mov_b64_e32 v[8:9], v[82:83]
	v_cmp_gt_i32_e32 vcc, 0, v14
	v_lshlrev_b32_e32 v13, 1, v13
	v_and_b32_e32 v14, 12, v13
	s_mov_b32 s13, 0x1000504
	v_mul_u32_u24_e32 v13, 0x1180, v55
	s_mov_b32 s14, 0x3020706
	v_add_u32_e32 v51, 0x200, v50
	v_cndmask_b32_e64 v2, v2, 0, vcc
	v_cndmask_b32_e64 v3, v3, 0, vcc
	v_cndmask_b32_e64 v0, v9, 0, vcc
	v_bitop3_b32 v9, v12, v50, 15 bitop3:0x78
	v_cndmask_b32_e64 v6, v6, 0, vcc
	v_lshl_add_u32 v9, v9, 4, 0
	v_cndmask_b32_e64 v7, v7, 0, vcc
	v_perm_b32 v15, v2, v6, s13
	v_add3_u32 v9, v9, v14, v13
	v_perm_b32 v2, v2, v6, s14
	v_cndmask_b32_e64 v8, v8, 0, vcc
	v_cndmask_b32_e64 v4, v4, 0, vcc
	ds_write2_b32 v9, v15, v2 offset1:140
	v_perm_b32 v2, v3, v7, s13
	v_perm_b32 v3, v3, v7, s14
	v_add_u32_e32 v6, 0x400, v9
	v_cndmask_b32_e64 v5, v5, 0, vcc
	ds_write2_b32 v6, v2, v3 offset0:24 offset1:164
	v_perm_b32 v2, v4, v8, s13
	v_perm_b32 v3, v4, v8, s14
	v_add_u32_e32 v4, 0x800, v9
	ds_write2_b32 v4, v2, v3 offset0:48 offset1:188
	v_perm_b32 v2, v5, v0, s13
	v_perm_b32 v0, v5, v0, s14
	v_add_u32_e32 v3, 0xc00, v9
	v_ashrrev_i32_e32 v14, 3, v51
	ds_write2_b32 v3, v2, v0 offset0:72 offset1:212
	v_and_b32_e32 v0, -2, v14
	v_add_u32_e32 v15, s12, v0
	v_max_i32_e32 v0, 0, v15
	v_lshlrev_b64 v[2:3], s22, v[0:1]
	v_or_b32_e32 v0, 1, v0
	v_lshlrev_b64 v[6:7], s22, v[0:1]
	v_lshl_add_u64 v[2:3], v[2:3], 0, s[18:19]
	v_lshl_add_u64 v[6:7], v[6:7], 0, s[18:19]
	v_mad_u64_u32 v[4:5], s[2:3], v2, s89, v[10:11]
	v_mad_u64_u32 v[8:9], s[2:3], v6, s89, v[10:11]
	v_mad_u32_u24 v5, v3, s89, v5
	v_mad_u32_u24 v9, v7, s89, v9
	s_waitcnt vmcnt(12)
	v_mov_b64_e32 v[2:3], v[84:85]
	v_mov_b64_e32 v[4:5], v[86:87]
	v_cmp_gt_i32_e32 vcc, 0, v15
	v_mov_b64_e32 v[6:7], v[88:89]
	v_mov_b64_e32 v[8:9], v[90:91]
	v_lshlrev_b32_e32 v14, 1, v14
	v_and_b32_e32 v14, 12, v14
	v_cndmask_b32_e64 v2, v2, 0, vcc
	v_cndmask_b32_e64 v3, v3, 0, vcc
	v_cndmask_b32_e64 v0, v9, 0, vcc
	v_ashrrev_i32_e32 v9, 6, v51
	v_bitop3_b32 v9, v9, v50, 15 bitop3:0x78
	v_cndmask_b32_e64 v6, v6, 0, vcc
	v_lshl_add_u32 v9, v9, 4, 0
	v_cndmask_b32_e64 v7, v7, 0, vcc
	v_perm_b32 v15, v2, v6, s13
	v_add3_u32 v9, v9, v14, v13
	v_perm_b32 v2, v2, v6, s14
	v_cndmask_b32_e64 v8, v8, 0, vcc
	v_cndmask_b32_e64 v4, v4, 0, vcc
	ds_write2_b32 v9, v15, v2 offset1:140
	v_perm_b32 v2, v3, v7, s13
	v_perm_b32 v3, v3, v7, s14
	v_add_u32_e32 v6, 0x400, v9
	v_cndmask_b32_e64 v5, v5, 0, vcc
	ds_write2_b32 v6, v2, v3 offset0:24 offset1:164
	v_perm_b32 v2, v4, v8, s13
	v_perm_b32 v3, v4, v8, s14
	v_add_u32_e32 v4, 0x800, v9
	v_add_u32_e32 v14, 0x400, v50
	ds_write2_b32 v4, v2, v3 offset0:48 offset1:188
	v_perm_b32 v2, v5, v0, s13
	v_perm_b32 v0, v5, v0, s14
	v_add_u32_e32 v3, 0xc00, v9
	v_ashrrev_i32_e32 v15, 3, v14
	ds_write2_b32 v3, v2, v0 offset0:72 offset1:212
	v_and_b32_e32 v0, -2, v15
	v_add_u32_e32 v16, s12, v0
	v_max_i32_e32 v0, 0, v16
	v_lshlrev_b64 v[2:3], s22, v[0:1]
	v_or_b32_e32 v0, 1, v0
	v_lshlrev_b64 v[6:7], s22, v[0:1]
	v_lshl_add_u64 v[2:3], v[2:3], 0, s[18:19]
	v_lshl_add_u64 v[6:7], v[6:7], 0, s[18:19]
	v_mad_u64_u32 v[4:5], s[2:3], v2, s89, v[10:11]
	v_mad_u64_u32 v[8:9], s[2:3], v6, s89, v[10:11]
	v_mad_u32_u24 v5, v3, s89, v5
	v_mad_u32_u24 v9, v7, s89, v9
	s_waitcnt vmcnt(10)
	v_mov_b64_e32 v[2:3], v[92:93]
	v_mov_b64_e32 v[4:5], v[94:95]
	v_cmp_gt_i32_e32 vcc, 0, v16
	v_mov_b64_e32 v[6:7], v[96:97]
	v_mov_b64_e32 v[8:9], v[98:99]
	v_lshlrev_b32_e32 v15, 1, v15
	v_and_b32_e32 v15, 12, v15
	v_cndmask_b32_e64 v2, v2, 0, vcc
	v_cndmask_b32_e64 v3, v3, 0, vcc
	v_cndmask_b32_e64 v0, v9, 0, vcc
	v_ashrrev_i32_e32 v9, 6, v14
	v_bitop3_b32 v9, v9, v50, 15 bitop3:0x78
	v_cndmask_b32_e64 v6, v6, 0, vcc
	v_lshl_add_u32 v9, v9, 4, 0
	v_cndmask_b32_e64 v7, v7, 0, vcc
	v_perm_b32 v16, v2, v6, s13
	v_add3_u32 v9, v9, v15, v13
	v_perm_b32 v2, v2, v6, s14
	v_cndmask_b32_e64 v8, v8, 0, vcc
	v_cndmask_b32_e64 v4, v4, 0, vcc
	ds_write2_b32 v9, v16, v2 offset1:140
	v_perm_b32 v2, v3, v7, s13
	v_perm_b32 v3, v3, v7, s14
	v_add_u32_e32 v6, 0x400, v9
	v_cndmask_b32_e64 v5, v5, 0, vcc
	ds_write2_b32 v6, v2, v3 offset0:24 offset1:164
	v_perm_b32 v2, v4, v8, s13
	v_perm_b32 v3, v4, v8, s14
	v_add_u32_e32 v4, 0x800, v9
	v_add_u32_e32 v15, 0x600, v50
	ds_write2_b32 v4, v2, v3 offset0:48 offset1:188
	v_perm_b32 v2, v5, v0, s13
	v_perm_b32 v0, v5, v0, s14
	v_add_u32_e32 v3, 0xc00, v9
	v_ashrrev_i32_e32 v16, 3, v15
	ds_write2_b32 v3, v2, v0 offset0:72 offset1:212
	v_and_b32_e32 v0, -2, v16
	v_add_u32_e32 v17, s12, v0
	v_max_i32_e32 v0, 0, v17
	v_lshlrev_b64 v[2:3], s22, v[0:1]
	v_or_b32_e32 v0, 1, v0
	v_lshlrev_b64 v[6:7], s22, v[0:1]
	v_lshl_add_u64 v[2:3], v[2:3], 0, s[18:19]
	v_lshl_add_u64 v[6:7], v[6:7], 0, s[18:19]
	v_mad_u64_u32 v[4:5], s[2:3], v2, s89, v[10:11]
	v_mad_u64_u32 v[8:9], s[2:3], v6, s89, v[10:11]
	v_mad_u32_u24 v5, v3, s89, v5
	v_mad_u32_u24 v9, v7, s89, v9
	s_waitcnt vmcnt(8)
; __device__ void swa_item(const Params& p, int item) {
;     ...
;   _Pragma("unroll") for (int i = 0; i < 4; ++i) {
;     int co = tid + 512 * i; int c8 = co & 15, kp = co >> 4;
;     int j0 = qb * 128 - 128 + 2 * kp;
;     const int j0c = (j0 >= 0) ? j0 : 0;
;     bf16x8 v0 = *(const bf16x8*)(buf + (rowb + (long)j0c * dil + r) * 4608 + vcol + c8 * 8);
;     bf16x8 v1 = *(const bf16x8*)(buf + (rowb + (long)(j0c + 1) * dil + r) * 4608 + vcol + c8 * 8);
;     if (j0 < 0) { v0 = (bf16x8){0, 0, 0, 0, 0, 0, 0, 0}; v1 = v0; }
;     const int chs = ((kp >> 2) ^ c8) * 8 + ((2 * kp) & 7);
;     _Pragma("unroll") for (int e = 0; e < 8; ++e)
;       *(unsigned*)(Vt + (c8 * 8 + e) * 280 + chs) = (unsigned)(bfu)v0[e] | ((unsigned)(bfu)v1[e] << 16);
;   }
;   _Pragma("unroll") for (int i = 0; i < 8; ++i) {
;     int co = tid + 512 * i; int c8 = co & 15, kj = co >> 4;
;     int j = qb * 128 - 128 + kj; j = (j >= 0) ? j : 0;
;     *(bf16x8*)(Ks + kj * 136 + c8 * 8) = *(const bf16x8*)(buf + (rowb + (long)j * dil + r) * 4608 + kcol + c8 * 8);
;   }
;   for (int i = tid; i < 128 * 12; i += NTHR) { int dv = i / 12, k2 = i % 12; *(unsigned*)(Vt + dv * 280 + 256 + 2 * k2) = 0u; }
	v_mov_b64_e32 v[2:3], v[100:101]
	v_mov_b64_e32 v[4:5], v[102:103]
	v_cmp_gt_i32_e32 vcc, 0, v17
	v_mov_b64_e32 v[6:7], v[104:105]
	v_mov_b64_e32 v[8:9], v[106:107]
	v_lshlrev_b32_e32 v10, 1, v16
	v_and_b32_e32 v10, 12, v10
	v_readlane_b32 s2, v254, 10
	v_cndmask_b32_e64 v2, v2, 0, vcc
	v_cndmask_b32_e64 v3, v3, 0, vcc
	v_cndmask_b32_e64 v0, v9, 0, vcc
	v_ashrrev_i32_e32 v9, 6, v15
	v_bitop3_b32 v9, v9, v50, 15 bitop3:0x78
	v_cndmask_b32_e64 v6, v6, 0, vcc
	v_lshl_add_u32 v9, v9, 4, 0
	v_cndmask_b32_e64 v7, v7, 0, vcc
	v_perm_b32 v11, v2, v6, s13
	v_add3_u32 v9, v9, v10, v13
	v_perm_b32 v2, v2, v6, s14
	v_cndmask_b32_e64 v8, v8, 0, vcc
	v_cndmask_b32_e64 v4, v4, 0, vcc
	ds_write2_b32 v9, v11, v2 offset1:140
	v_perm_b32 v2, v3, v7, s13
	v_perm_b32 v3, v3, v7, s14
	v_add_u32_e32 v6, 0x400, v9
	v_cndmask_b32_e64 v5, v5, 0, vcc
	ds_write2_b32 v6, v2, v3 offset0:24 offset1:164
	v_perm_b32 v2, v4, v8, s13
	v_perm_b32 v3, v4, v8, s14
	v_add_u32_e32 v4, 0x800, v9
	ds_write2_b32 v4, v2, v3 offset0:48 offset1:188
	v_perm_b32 v2, v5, v0, s13
	v_perm_b32 v0, v5, v0, s14
	v_add_u32_e32 v3, 0xc00, v9
	v_ashrrev_i32_e32 v7, 4, v50
	ds_write2_b32 v3, v2, v0 offset0:72 offset1:212
	v_add_u32_e32 v2, s12, v7
	v_lshlrev_b32_e32 v0, 3, v50
	v_max_i32_e32 v2, 0, v2
	v_mov_b32_e32 v3, v1
	v_and_b32_e32 v0, 0x78, v0
	v_lshlrev_b64 v[2:3], s22, v[2:3]
	v_lshlrev_b32_e32 v0, 1, v0
	v_lshl_add_u64 v[2:3], v[2:3], 0, s[18:19]
	v_mov_b64_e32 v[8:9], s[52:53]
	v_add_u32_e32 v6, s2, v0
	v_mad_u64_u32 v[4:5], s[2:3], v2, s89, v[8:9]
	v_mad_u32_u24 v5, v3, s89, v5
	v_lshl_add_u64 v[2:3], v[4:5], 0, v[0:1]
	s_waitcnt vmcnt(7)
	v_mov_b64_e32 v[2:3], v[108:109]
	v_mov_b64_e32 v[4:5], v[110:111]
	s_movk_i32 s13, 0x110
	v_mad_u64_u32 v[10:11], s[2:3], v7, s13, v[6:7]
	v_ashrrev_i32_e32 v7, 4, v51
	ds_write_b128 v10, v[2:5]
	v_add_u32_e32 v2, s12, v7
	v_max_i32_e32 v2, 0, v2
	v_mov_b32_e32 v3, v1
	v_lshlrev_b64 v[2:3], s22, v[2:3]
	v_lshl_add_u64 v[2:3], v[2:3], 0, s[18:19]
	v_mad_u64_u32 v[4:5], s[2:3], v2, s89, v[8:9]
	v_mad_u32_u24 v5, v3, s89, v5
	v_lshl_add_u64 v[2:3], v[4:5], 0, v[0:1]
	s_waitcnt vmcnt(6)
	v_mov_b64_e32 v[2:3], v[112:113]
	v_mov_b64_e32 v[4:5], v[114:115]
	v_mad_u64_u32 v[10:11], s[2:3], v7, s13, v[6:7]
	v_ashrrev_i32_e32 v7, 4, v14
	ds_write_b128 v10, v[2:5]
	v_add_u32_e32 v2, s12, v7
	v_max_i32_e32 v2, 0, v2
	v_mov_b32_e32 v3, v1
	v_lshlrev_b64 v[2:3], s22, v[2:3]
	v_lshl_add_u64 v[2:3], v[2:3], 0, s[18:19]
	v_mad_u64_u32 v[4:5], s[2:3], v2, s89, v[8:9]
	v_mad_u32_u24 v5, v3, s89, v5
	v_lshl_add_u64 v[2:3], v[4:5], 0, v[0:1]
	s_waitcnt vmcnt(5)
	v_mov_b64_e32 v[2:3], v[116:117]
	v_mov_b64_e32 v[4:5], v[118:119]
	v_mad_u64_u32 v[10:11], s[2:3], v7, s13, v[6:7]
	v_ashrrev_i32_e32 v7, 4, v15
	ds_write_b128 v10, v[2:5]
	v_add_u32_e32 v2, s12, v7
	v_max_i32_e32 v2, 0, v2
	v_mov_b32_e32 v3, v1
	v_lshlrev_b64 v[2:3], s22, v[2:3]
	v_lshl_add_u64 v[2:3], v[2:3], 0, s[18:19]
	v_mad_u64_u32 v[4:5], s[2:3], v2, s89, v[8:9]
	v_mad_u32_u24 v5, v3, s89, v5
	v_lshl_add_u64 v[2:3], v[4:5], 0, v[0:1]
	s_waitcnt vmcnt(4)
	v_mov_b64_e32 v[2:3], v[120:121]
	v_mov_b64_e32 v[4:5], v[122:123]
	v_mad_u64_u32 v[10:11], s[2:3], v7, s13, v[6:7]
	ds_write_b128 v10, v[2:5]
	v_add_u32_e32 v2, 0x800, v50
	v_ashrrev_i32_e32 v7, 4, v2
	v_add_u32_e32 v2, s12, v7
	v_max_i32_e32 v2, 0, v2
	v_mov_b32_e32 v3, v1
	v_lshlrev_b64 v[2:3], s22, v[2:3]
	v_lshl_add_u64 v[2:3], v[2:3], 0, s[18:19]
	v_mad_u64_u32 v[4:5], s[2:3], v2, s89, v[8:9]
	v_mad_u32_u24 v5, v3, s89, v5
	v_lshl_add_u64 v[2:3], v[4:5], 0, v[0:1]
	s_waitcnt vmcnt(3)
	v_mov_b64_e32 v[2:3], v[124:125]
	v_mov_b64_e32 v[4:5], v[126:127]
	v_mad_u64_u32 v[10:11], s[2:3], v7, s13, v[6:7]
	ds_write_b128 v10, v[2:5]
	v_add_u32_e32 v2, 0xa00, v50
	v_ashrrev_i32_e32 v7, 4, v2
	v_add_u32_e32 v2, s12, v7
	v_max_i32_e32 v2, 0, v2
	v_mov_b32_e32 v3, v1
	v_lshlrev_b64 v[2:3], s22, v[2:3]
	v_lshl_add_u64 v[2:3], v[2:3], 0, s[18:19]
	v_mad_u64_u32 v[4:5], s[2:3], v2, s89, v[8:9]
	v_mad_u32_u24 v5, v3, s89, v5
	v_lshl_add_u64 v[2:3], v[4:5], 0, v[0:1]
	s_waitcnt vmcnt(2)
	v_mov_b64_e32 v[2:3], v[128:129]
	v_mov_b64_e32 v[4:5], v[130:131]
	v_mad_u64_u32 v[10:11], s[2:3], v7, s13, v[6:7]
	ds_write_b128 v10, v[2:5]
	v_add_u32_e32 v2, 0xc00, v50
	v_ashrrev_i32_e32 v7, 4, v2
	v_add_u32_e32 v2, s12, v7
	v_max_i32_e32 v2, 0, v2
	v_mov_b32_e32 v3, v1
	v_lshlrev_b64 v[2:3], s22, v[2:3]
	v_lshl_add_u64 v[2:3], v[2:3], 0, s[18:19]
	v_mad_u64_u32 v[4:5], s[2:3], v2, s89, v[8:9]
	v_mad_u32_u24 v5, v3, s89, v5
	v_lshl_add_u64 v[2:3], v[4:5], 0, v[0:1]
	s_waitcnt vmcnt(1)
	v_mov_b64_e32 v[2:3], v[132:133]
	v_mov_b64_e32 v[4:5], v[134:135]
	v_mad_u64_u32 v[10:11], s[2:3], v7, s13, v[6:7]
	v_writelane_b32 v254, s18, 13
	ds_write_b128 v10, v[2:5]
	v_add_u32_e32 v2, 0xe00, v50
	v_ashrrev_i32_e32 v7, 4, v2
	v_add_u32_e32 v2, s12, v7
	v_max_i32_e32 v2, 0, v2
	v_mov_b32_e32 v3, v1
	v_lshlrev_b64 v[2:3], s22, v[2:3]
	v_lshl_add_u64 v[2:3], v[2:3], 0, s[18:19]
	v_mad_u64_u32 v[4:5], s[2:3], v2, s89, v[8:9]
	v_mad_u32_u24 v5, v3, s89, v5
	v_lshl_add_u64 v[2:3], v[4:5], 0, v[0:1]
	s_waitcnt vmcnt(0)
	v_mov_b64_e32 v[2:3], v[136:137]
	v_mov_b64_e32 v[4:5], v[138:139]
	v_mad_u64_u32 v[6:7], s[2:3], v7, s13, v[6:7]
	s_movk_i32 s2, 0x600
	v_writelane_b32 v254, s19, 14
	v_cmp_gt_i32_e32 vcc, s2, v50
	ds_write_b128 v6, v[2:5]
	s_and_saveexec_b64 s[12:13], vcc
	s_cbranch_execz .LBB0_111
	v_max_i32_e32 v2, 0x400, v50
	v_sub_u32_e32 v2, v2, v50
	v_add_u32_e32 v3, 0x1ff, v2
	v_cmp_lt_u32_e32 vcc, s24, v3
	s_mov_b64 s[18:19], -1
	v_mov_b32_e32 v2, v50
	s_and_saveexec_b64 s[14:15], vcc
	s_cbranch_execz .LBB0_108
	v_lshrrev_b32_e32 v2, 9, v3
	v_add_u32_e32 v4, 1, v2
	v_and_b32_e32 v5, 0xfffffe, v4
	s_mov_b64 s[18:19], 0
	v_mov_b32_e32 v6, v5
	v_mov_b64_e32 v[2:3], v[50:51]
	s_mov_b32 s2, 0x2aaaaaab
	s_movk_i32 s3, 0x230

; __device__ void dn_pre_item(const Params& p, int L, int idx) {
;     ...
;   } else {
;     for (int e = tid - 64; e < 16384; e += 448) {
;       const int col = e >> 6, s = e & 63;
;       float v = (col < 128) ? betas[s] * vs[s * 132 + col] : betas[s] * egc[s] * ks[s * 132 + (col - 128)];
;       rhsT[col * 72 + s] = f2bf(v);
;     }
.LBB0_560:
	s_or_b64 exec, exec, s[0:1]
	s_barrier
	s_and_saveexec_b64 s[0:1], s[38:39]
	s_xor_b64 s[0:1], exec, s[0:1]
	s_cbranch_execz .LBB0_569
	v_and_b32_e32 v112, 63, v40
	v_lshl_add_u32 v113, v112, 2, v20
	ds_read_b32 v114, v113 offset:16896
	ds_read_b32 v115, v113 offset:17152
	s_lshr_b32 s12, s33, 6
	s_add_i32 s12, s12, -1
	s_movk_i32 s2, 0x210
	v_mad_u32_u24 v116, v112, s2, v20
	s_lshl_b32 s13, s12, 2
	v_add_u32_e32 v116, s13, v116
	s_mul_i32 s13, s12, 0x90
	s_add_i32 s13, s13, 0x1d000
	v_lshl_add_u32 v117, v112, 1, v20
	v_add_u32_e32 v117, s13, v117
	s_waitcnt lgkmcnt(0)
	v_mul_f32_e32 v115, v114, v115
	s_add_i32 s15, s12, 0
	s_mov_b32 s14, 0xc600
	s_cmp_lt_u32 s15, 128
	s_cselect_b32 s14, 0x14c00, s14
	s_add_i32 s14, s14, 0
	v_add_u32_e32 v118, s14, v116
	ds_read_b32 v120, v118
	s_add_i32 s15, s12, 7
	s_mov_b32 s14, 0xc600
	s_cmp_lt_u32 s15, 128
	s_cselect_b32 s14, 0x14c00, s14
	s_add_i32 s14, s14, 28
	v_add_u32_e32 v118, s14, v116
	ds_read_b32 v121, v118
	s_add_i32 s15, s12, 14
	s_mov_b32 s14, 0xc600
	s_cmp_lt_u32 s15, 128
	s_cselect_b32 s14, 0x14c00, s14
	s_add_i32 s14, s14, 56
	v_add_u32_e32 v118, s14, v116
	ds_read_b32 v122, v118
	s_add_i32 s15, s12, 21
	s_mov_b32 s14, 0xc600
	s_cmp_lt_u32 s15, 128
	s_cselect_b32 s14, 0x14c00, s14
	s_add_i32 s14, s14, 84
	v_add_u32_e32 v118, s14, v116
	ds_read_b32 v123, v118
	s_add_i32 s15, s12, 28
	s_mov_b32 s14, 0xc600
	s_cmp_lt_u32 s15, 128
	s_cselect_b32 s14, 0x14c00, s14
	s_add_i32 s14, s14, 112
	v_add_u32_e32 v118, s14, v116
	ds_read_b32 v124, v118
	s_add_i32 s15, s12, 35
	s_mov_b32 s14, 0xc600
	s_cmp_lt_u32 s15, 128
	s_cselect_b32 s14, 0x14c00, s14
	s_add_i32 s14, s14, 140
	v_add_u32_e32 v118, s14, v116
	ds_read_b32 v125, v118
	s_add_i32 s15, s12, 42
	s_mov_b32 s14, 0xc600
	s_cmp_lt_u32 s15, 128
	s_cselect_b32 s14, 0x14c00, s14
	s_add_i32 s14, s14, 168
	v_add_u32_e32 v118, s14, v116
	ds_read_b32 v126, v118
	s_add_i32 s15, s12, 49
	s_mov_b32 s14, 0xc600
	s_cmp_lt_u32 s15, 128
	s_cselect_b32 s14, 0x14c00, s14
	s_add_i32 s14, s14, 196
	v_add_u32_e32 v118, s14, v116
	ds_read_b32 v127, v118
	s_waitcnt lgkmcnt(7)
	s_add_i32 s15, s12, 0
	s_cmp_lt_u32 s15, 128
	s_cselect_b64 s[18:19], -1, 0
	v_cndmask_b32_e64 v119, v115, v114, s[18:19]
	v_mul_f32_e32 v119, v119, v120
	v_cvt_pk_bf16_f32 v119, v119, v119
	ds_write_b16 v117, v119 offset:0
	s_add_i32 s15, s12, 56
	s_mov_b32 s14, 0xc600
	s_cmp_lt_u32 s15, 128
	s_cselect_b32 s14, 0x14c00, s14
	s_add_i32 s14, s14, 224
	v_add_u32_e32 v118, s14, v116
	ds_read_b32 v120, v118
	s_waitcnt lgkmcnt(8)
	s_add_i32 s15, s12, 7
	s_cmp_lt_u32 s15, 128
	s_cselect_b64 s[18:19], -1, 0
	v_cndmask_b32_e64 v119, v115, v114, s[18:19]
	v_mul_f32_e32 v119, v119, v121
	v_cvt_pk_bf16_f32 v119, v119, v119
	ds_write_b16 v117, v119 offset:1008
	s_add_i32 s15, s12, 63
	s_mov_b32 s14, 0xc600
	s_cmp_lt_u32 s15, 128
	s_cselect_b32 s14, 0x14c00, s14
	s_add_i32 s14, s14, 252
	v_add_u32_e32 v118, s14, v116
	ds_read_b32 v121, v118
	s_waitcnt lgkmcnt(9)
	s_add_i32 s15, s12, 14
	s_cmp_lt_u32 s15, 128
	s_cselect_b64 s[18:19], -1, 0
	v_cndmask_b32_e64 v119, v115, v114, s[18:19]
	v_mul_f32_e32 v119, v119, v122
	v_cvt_pk_bf16_f32 v119, v119, v119
	ds_write_b16 v117, v119 offset:2016
	s_add_i32 s15, s12, 70
	s_mov_b32 s14, 0xc600
	s_cmp_lt_u32 s15, 128
	s_cselect_b32 s14, 0x14c00, s14
	s_add_i32 s14, s14, 280
	v_add_u32_e32 v118, s14, v116
	ds_read_b32 v122, v118
	s_waitcnt lgkmcnt(10)
	s_add_i32 s15, s12, 21
	s_cmp_lt_u32 s15, 128
	s_cselect_b64 s[18:19], -1, 0
	v_cndmask_b32_e64 v119, v115, v114, s[18:19]
	v_mul_f32_e32 v119, v119, v123
	v_cvt_pk_bf16_f32 v119, v119, v119
	ds_write_b16 v117, v119 offset:3024
	s_add_i32 s15, s12, 77
	s_mov_b32 s14, 0xc600
	s_cmp_lt_u32 s15, 128
	s_cselect_b32 s14, 0x14c00, s14
	s_add_i32 s14, s14, 308
	v_add_u32_e32 v118, s14, v116
	ds_read_b32 v123, v118
	s_waitcnt lgkmcnt(11)
	s_add_i32 s15, s12, 28
	s_cmp_lt_u32 s15, 128
	s_cselect_b64 s[18:19], -1, 0
	v_cndmask_b32_e64 v119, v115, v114, s[18:19]
	v_mul_f32_e32 v119, v119, v124
	v_cvt_pk_bf16_f32 v119, v119, v119
	ds_write_b16 v117, v119 offset:4032
	s_add_i32 s15, s12, 84
	s_mov_b32 s14, 0xc600
	s_cmp_lt_u32 s15, 128
	s_cselect_b32 s14, 0x14c00, s14
	s_add_i32 s14, s14, 336
	v_add_u32_e32 v118, s14, v116
	ds_read_b32 v124, v118
	s_waitcnt lgkmcnt(12)
	s_add_i32 s15, s12, 35
	s_cmp_lt_u32 s15, 128
	s_cselect_b64 s[18:19], -1, 0
	v_cndmask_b32_e64 v119, v115, v114, s[18:19]
	v_mul_f32_e32 v119, v119, v125
	v_cvt_pk_bf16_f32 v119, v119, v119
	ds_write_b16 v117, v119 offset:5040
	s_add_i32 s15, s12, 91
	s_mov_b32 s14, 0xc600
	s_cmp_lt_u32 s15, 128
	s_cselect_b32 s14, 0x14c00, s14
	s_add_i32 s14, s14, 364
	v_add_u32_e32 v118, s14, v116
	ds_read_b32 v125, v118
	s_waitcnt lgkmcnt(13)
	s_add_i32 s15, s12, 42
	s_cmp_lt_u32 s15, 128
	s_cselect_b64 s[18:19], -1, 0
	v_cndmask_b32_e64 v119, v115, v114, s[18:19]
	v_mul_f32_e32 v119, v119, v126
	v_cvt_pk_bf16_f32 v119, v119, v119
	ds_write_b16 v117, v119 offset:6048
	s_add_i32 s15, s12, 98
	s_mov_b32 s14, 0xc600
	s_cmp_lt_u32 s15, 128
	s_cselect_b32 s14, 0x14c00, s14
	s_add_i32 s14, s14, 392
	v_add_u32_e32 v118, s14, v116
	ds_read_b32 v126, v118
	s_waitcnt lgkmcnt(14)
	s_add_i32 s15, s12, 49
	s_cmp_lt_u32 s15, 128
	s_cselect_b64 s[18:19], -1, 0
	v_cndmask_b32_e64 v119, v115, v114, s[18:19]
	v_mul_f32_e32 v119, v119, v127
	v_cvt_pk_bf16_f32 v119, v119, v119
	ds_write_b16 v117, v119 offset:7056
	s_add_i32 s15, s12, 105
	s_mov_b32 s14, 0xc600
	s_cmp_lt_u32 s15, 128
	s_cselect_b32 s14, 0x14c00, s14
	s_add_i32 s14, s14, 420
	v_add_u32_e32 v118, s14, v116
	ds_read_b32 v127, v118
	s_waitcnt lgkmcnt(14)
; __device__ void dn_pre_item(const Params& p, int L, int idx) {
;     ...
;   } else {
;     for (int e = tid - 64; e < 16384; e += 448) {
;       const int col = e >> 6, s = e & 63;
;       float v = (col < 128) ? betas[s] * vs[s * 132 + col] : betas[s] * egc[s] * ks[s * 132 + (col - 128)];
;       rhsT[col * 72 + s] = f2bf(v);
;     }
	s_add_i32 s15, s12, 56
	s_cmp_lt_u32 s15, 128
	s_cselect_b64 s[18:19], -1, 0
	v_cndmask_b32_e64 v119, v115, v114, s[18:19]
	v_mul_f32_e32 v119, v119, v120
	v_cvt_pk_bf16_f32 v119, v119, v119
	ds_write_b16 v117, v119 offset:8064
	s_add_i32 s15, s12, 112
	s_mov_b32 s14, 0xc600
	s_cmp_lt_u32 s15, 128
	s_cselect_b32 s14, 0x14c00, s14
	s_add_i32 s14, s14, 448
	v_add_u32_e32 v118, s14, v116
	ds_read_b32 v120, v118
	s_waitcnt lgkmcnt(14)
	s_add_i32 s15, s12, 63
	s_cmp_lt_u32 s15, 128
	s_cselect_b64 s[18:19], -1, 0
	v_cndmask_b32_e64 v119, v115, v114, s[18:19]
	v_mul_f32_e32 v119, v119, v121
	v_cvt_pk_bf16_f32 v119, v119, v119
	ds_write_b16 v117, v119 offset:9072
	s_add_i32 s15, s12, 119
	s_mov_b32 s14, 0xc600
	s_cmp_lt_u32 s15, 128
	s_cselect_b32 s14, 0x14c00, s14
	s_add_i32 s14, s14, 476
	v_add_u32_e32 v118, s14, v116
	ds_read_b32 v121, v118
	s_waitcnt lgkmcnt(14)
	s_add_i32 s15, s12, 70
	s_cmp_lt_u32 s15, 128
	s_cselect_b64 s[18:19], -1, 0
	v_cndmask_b32_e64 v119, v115, v114, s[18:19]
	v_mul_f32_e32 v119, v119, v122
	v_cvt_pk_bf16_f32 v119, v119, v119
	ds_write_b16 v117, v119 offset:10080
	s_add_i32 s15, s12, 126
	s_mov_b32 s14, 0xc600
	s_cmp_lt_u32 s15, 128
	s_cselect_b32 s14, 0x14c00, s14
	s_add_i32 s14, s14, 504
	v_add_u32_e32 v118, s14, v116
	ds_read_b32 v122, v118
	s_waitcnt lgkmcnt(14)
	s_add_i32 s15, s12, 77
	s_cmp_lt_u32 s15, 128
	s_cselect_b64 s[18:19], -1, 0
	v_cndmask_b32_e64 v119, v115, v114, s[18:19]
	v_mul_f32_e32 v119, v119, v123
	v_cvt_pk_bf16_f32 v119, v119, v119
	ds_write_b16 v117, v119 offset:11088
	s_add_i32 s15, s12, 133
	s_mov_b32 s14, 0xc600
	s_cmp_lt_u32 s15, 128
	s_cselect_b32 s14, 0x14c00, s14
	s_add_i32 s14, s14, 532
	v_add_u32_e32 v118, s14, v116
	ds_read_b32 v123, v118
	s_waitcnt lgkmcnt(14)
	s_add_i32 s15, s12, 84
	s_cmp_lt_u32 s15, 128
	s_cselect_b64 s[18:19], -1, 0
	v_cndmask_b32_e64 v119, v115, v114, s[18:19]
	v_mul_f32_e32 v119, v119, v124
	v_cvt_pk_bf16_f32 v119, v119, v119
	ds_write_b16 v117, v119 offset:12096
	s_add_i32 s15, s12, 140
	s_mov_b32 s14, 0xc600
	s_cmp_lt_u32 s15, 128
	s_cselect_b32 s14, 0x14c00, s14
	s_add_i32 s14, s14, 560
	v_add_u32_e32 v118, s14, v116
	ds_read_b32 v124, v118
	s_waitcnt lgkmcnt(14)
	s_add_i32 s15, s12, 91
	s_cmp_lt_u32 s15, 128
	s_cselect_b64 s[18:19], -1, 0
	v_cndmask_b32_e64 v119, v115, v114, s[18:19]
	v_mul_f32_e32 v119, v119, v125
	v_cvt_pk_bf16_f32 v119, v119, v119
	ds_write_b16 v117, v119 offset:13104
	s_add_i32 s15, s12, 147
	s_mov_b32 s14, 0xc600
	s_cmp_lt_u32 s15, 128
	s_cselect_b32 s14, 0x14c00, s14
	s_add_i32 s14, s14, 588
	v_add_u32_e32 v118, s14, v116
	ds_read_b32 v125, v118
	s_waitcnt lgkmcnt(14)
	s_add_i32 s15, s12, 98
	s_cmp_lt_u32 s15, 128
	s_cselect_b64 s[18:19], -1, 0
	v_cndmask_b32_e64 v119, v115, v114, s[18:19]
	v_mul_f32_e32 v119, v119, v126
	v_cvt_pk_bf16_f32 v119, v119, v119
	ds_write_b16 v117, v119 offset:14112
	s_add_i32 s15, s12, 154
	s_mov_b32 s14, 0xc600
	s_cmp_lt_u32 s15, 128
	s_cselect_b32 s14, 0x14c00, s14
	s_add_i32 s14, s14, 616
	v_add_u32_e32 v118, s14, v116
	ds_read_b32 v126, v118
	s_waitcnt lgkmcnt(14)
	s_add_i32 s15, s12, 105
	s_cmp_lt_u32 s15, 128
	s_cselect_b64 s[18:19], -1, 0
	v_cndmask_b32_e64 v119, v115, v114, s[18:19]
	v_mul_f32_e32 v119, v119, v127
	v_cvt_pk_bf16_f32 v119, v119, v119
	ds_write_b16 v117, v119 offset:15120
	s_add_i32 s15, s12, 161
	s_mov_b32 s14, 0xc600
	s_cmp_lt_u32 s15, 128
	s_cselect_b32 s14, 0x14c00, s14
	s_add_i32 s14, s14, 644
	v_add_u32_e32 v118, s14, v116
	ds_read_b32 v127, v118
	s_waitcnt lgkmcnt(14)
	s_add_i32 s15, s12, 112
	s_cmp_lt_u32 s15, 128
	s_cselect_b64 s[18:19], -1, 0
	v_cndmask_b32_e64 v119, v115, v114, s[18:19]
	v_mul_f32_e32 v119, v119, v120
	v_cvt_pk_bf16_f32 v119, v119, v119
	ds_write_b16 v117, v119 offset:16128
	s_add_i32 s15, s12, 168
	s_mov_b32 s14, 0xc600
	s_cmp_lt_u32 s15, 128
	s_cselect_b32 s14, 0x14c00, s14
	s_add_i32 s14, s14, 672
	v_add_u32_e32 v118, s14, v116
	ds_read_b32 v120, v118
	s_waitcnt lgkmcnt(14)
	s_add_i32 s15, s12, 119
	s_cmp_lt_u32 s15, 128
	s_cselect_b64 s[18:19], -1, 0
	v_cndmask_b32_e64 v119, v115, v114, s[18:19]
	v_mul_f32_e32 v119, v119, v121
	v_cvt_pk_bf16_f32 v119, v119, v119
	ds_write_b16 v117, v119 offset:17136
	s_add_i32 s15, s12, 175
	s_mov_b32 s14, 0xc600
	s_cmp_lt_u32 s15, 128
	s_cselect_b32 s14, 0x14c00, s14
	s_add_i32 s14, s14, 700
	v_add_u32_e32 v118, s14, v116
	ds_read_b32 v121, v118
	s_waitcnt lgkmcnt(14)
	s_add_i32 s15, s12, 126
	s_cmp_lt_u32 s15, 128
	s_cselect_b64 s[18:19], -1, 0
	v_cndmask_b32_e64 v119, v115, v114, s[18:19]
	v_mul_f32_e32 v119, v119, v122
	v_cvt_pk_bf16_f32 v119, v119, v119
	ds_write_b16 v117, v119 offset:18144
	s_add_i32 s15, s12, 182
	s_mov_b32 s14, 0xc600
	s_cmp_lt_u32 s15, 128
	s_cselect_b32 s14, 0x14c00, s14
	s_add_i32 s14, s14, 728
	v_add_u32_e32 v118, s14, v116
	ds_read_b32 v122, v118
	s_waitcnt lgkmcnt(14)
	s_add_i32 s15, s12, 133
	s_cmp_lt_u32 s15, 128
	s_cselect_b64 s[18:19], -1, 0
	v_cndmask_b32_e64 v119, v115, v114, s[18:19]
	v_mul_f32_e32 v119, v119, v123
	v_cvt_pk_bf16_f32 v119, v119, v119
	ds_write_b16 v117, v119 offset:19152
	s_add_i32 s15, s12, 189
	s_mov_b32 s14, 0xc600
	s_cmp_lt_u32 s15, 128
	s_cselect_b32 s14, 0x14c00, s14
	s_add_i32 s14, s14, 756
	v_add_u32_e32 v118, s14, v116
	ds_read_b32 v123, v118
	s_waitcnt lgkmcnt(14)
	s_add_i32 s15, s12, 140
	s_cmp_lt_u32 s15, 128
	s_cselect_b64 s[18:19], -1, 0
	v_cndmask_b32_e64 v119, v115, v114, s[18:19]
	v_mul_f32_e32 v119, v119, v124
	v_cvt_pk_bf16_f32 v119, v119, v119
	ds_write_b16 v117, v119 offset:20160
	s_add_i32 s15, s12, 196
	s_mov_b32 s14, 0xc600
	s_cmp_lt_u32 s15, 128
	s_cselect_b32 s14, 0x14c00, s14
	s_add_i32 s14, s14, 784
	v_add_u32_e32 v118, s14, v116
	ds_read_b32 v124, v118
	s_waitcnt lgkmcnt(14)
; __device__ void dn_pre_item(const Params& p, int L, int idx) {
;     ...
;   } else {
;     for (int e = tid - 64; e < 16384; e += 448) {
;       const int col = e >> 6, s = e & 63;
;       float v = (col < 128) ? betas[s] * vs[s * 132 + col] : betas[s] * egc[s] * ks[s * 132 + (col - 128)];
;       rhsT[col * 72 + s] = f2bf(v);
;     }
	s_add_i32 s15, s12, 147
	s_cmp_lt_u32 s15, 128
	s_cselect_b64 s[18:19], -1, 0
	v_cndmask_b32_e64 v119, v115, v114, s[18:19]
	v_mul_f32_e32 v119, v119, v125
	v_cvt_pk_bf16_f32 v119, v119, v119
	ds_write_b16 v117, v119 offset:21168
	s_add_i32 s15, s12, 203
	s_mov_b32 s14, 0xc600
	s_cmp_lt_u32 s15, 128
	s_cselect_b32 s14, 0x14c00, s14
	s_add_i32 s14, s14, 812
	v_add_u32_e32 v118, s14, v116
	ds_read_b32 v125, v118
	s_waitcnt lgkmcnt(14)
	s_add_i32 s15, s12, 154
	s_cmp_lt_u32 s15, 128
	s_cselect_b64 s[18:19], -1, 0
	v_cndmask_b32_e64 v119, v115, v114, s[18:19]
	v_mul_f32_e32 v119, v119, v126
	v_cvt_pk_bf16_f32 v119, v119, v119
	ds_write_b16 v117, v119 offset:22176
	s_add_i32 s15, s12, 210
	s_mov_b32 s14, 0xc600
	s_cmp_lt_u32 s15, 128
	s_cselect_b32 s14, 0x14c00, s14
	s_add_i32 s14, s14, 840
	v_add_u32_e32 v118, s14, v116
	ds_read_b32 v126, v118
	s_waitcnt lgkmcnt(14)
	s_add_i32 s15, s12, 161
	s_cmp_lt_u32 s15, 128
	s_cselect_b64 s[18:19], -1, 0
	v_cndmask_b32_e64 v119, v115, v114, s[18:19]
	v_mul_f32_e32 v119, v119, v127
	v_cvt_pk_bf16_f32 v119, v119, v119
	ds_write_b16 v117, v119 offset:23184
	s_add_i32 s15, s12, 217
	s_mov_b32 s14, 0xc600
	s_cmp_lt_u32 s15, 128
	s_cselect_b32 s14, 0x14c00, s14
	s_add_i32 s14, s14, 868
	v_add_u32_e32 v118, s14, v116
	ds_read_b32 v127, v118
	s_waitcnt lgkmcnt(14)
	s_add_i32 s15, s12, 168
	s_cmp_lt_u32 s15, 128
	s_cselect_b64 s[18:19], -1, 0
	v_cndmask_b32_e64 v119, v115, v114, s[18:19]
	v_mul_f32_e32 v119, v119, v120
	v_cvt_pk_bf16_f32 v119, v119, v119
	ds_write_b16 v117, v119 offset:24192
	s_add_i32 s15, s12, 224
	s_mov_b32 s14, 0xc600
	s_cmp_lt_u32 s15, 128
	s_cselect_b32 s14, 0x14c00, s14
	s_add_i32 s14, s14, 896
	v_add_u32_e32 v118, s14, v116
	ds_read_b32 v120, v118
	s_waitcnt lgkmcnt(14)
	s_add_i32 s15, s12, 175
	s_cmp_lt_u32 s15, 128
	s_cselect_b64 s[18:19], -1, 0
	v_cndmask_b32_e64 v119, v115, v114, s[18:19]
	v_mul_f32_e32 v119, v119, v121
	v_cvt_pk_bf16_f32 v119, v119, v119
	ds_write_b16 v117, v119 offset:25200
	s_add_i32 s15, s12, 231
	s_mov_b32 s14, 0xc600
	s_cmp_lt_u32 s15, 128
	s_cselect_b32 s14, 0x14c00, s14
	s_add_i32 s14, s14, 924
	v_add_u32_e32 v118, s14, v116
	ds_read_b32 v121, v118
	s_waitcnt lgkmcnt(14)
	s_add_i32 s15, s12, 182
	s_cmp_lt_u32 s15, 128
	s_cselect_b64 s[18:19], -1, 0
	v_cndmask_b32_e64 v119, v115, v114, s[18:19]
	v_mul_f32_e32 v119, v119, v122
	v_cvt_pk_bf16_f32 v119, v119, v119
	ds_write_b16 v117, v119 offset:26208
	s_add_i32 s15, s12, 238
	s_mov_b32 s14, 0xc600
	s_cmp_lt_u32 s15, 128
	s_cselect_b32 s14, 0x14c00, s14
	s_add_i32 s14, s14, 952
	v_add_u32_e32 v118, s14, v116
	ds_read_b32 v122, v118
	s_waitcnt lgkmcnt(14)
	s_add_i32 s15, s12, 189
	s_cmp_lt_u32 s15, 128
	s_cselect_b64 s[18:19], -1, 0
	v_cndmask_b32_e64 v119, v115, v114, s[18:19]
	v_mul_f32_e32 v119, v119, v123
	v_cvt_pk_bf16_f32 v119, v119, v119
	ds_write_b16 v117, v119 offset:27216
	s_add_i32 s15, s12, 245
	s_mov_b32 s14, 0xc600
	s_cmp_lt_u32 s15, 128
	s_cselect_b32 s14, 0x14c00, s14
	s_add_i32 s14, s14, 980
	v_add_u32_e32 v118, s14, v116
	ds_read_b32 v123, v118
	s_waitcnt lgkmcnt(14)
	s_add_i32 s15, s12, 196
	s_cmp_lt_u32 s15, 128
	s_cselect_b64 s[18:19], -1, 0
	v_cndmask_b32_e64 v119, v115, v114, s[18:19]
	v_mul_f32_e32 v119, v119, v124
	v_cvt_pk_bf16_f32 v119, v119, v119
	ds_write_b16 v117, v119 offset:28224
	s_waitcnt lgkmcnt(13)
	s_add_i32 s15, s12, 203
	s_cmp_lt_u32 s15, 128
	s_cselect_b64 s[18:19], -1, 0
	v_cndmask_b32_e64 v119, v115, v114, s[18:19]
	v_mul_f32_e32 v119, v119, v125
	v_cvt_pk_bf16_f32 v119, v119, v119
	ds_write_b16 v117, v119 offset:29232
	s_waitcnt lgkmcnt(12)
	s_add_i32 s15, s12, 210
	s_cmp_lt_u32 s15, 128
	s_cselect_b64 s[18:19], -1, 0
	v_cndmask_b32_e64 v119, v115, v114, s[18:19]
	v_mul_f32_e32 v119, v119, v126
	v_cvt_pk_bf16_f32 v119, v119, v119
	ds_write_b16 v117, v119 offset:30240
	s_waitcnt lgkmcnt(11)
	s_add_i32 s15, s12, 217
	s_cmp_lt_u32 s15, 128
	s_cselect_b64 s[18:19], -1, 0
	v_cndmask_b32_e64 v119, v115, v114, s[18:19]
	v_mul_f32_e32 v119, v119, v127
	v_cvt_pk_bf16_f32 v119, v119, v119
	ds_write_b16 v117, v119 offset:31248
	s_waitcnt lgkmcnt(10)
	s_add_i32 s15, s12, 224
	s_cmp_lt_u32 s15, 128
	s_cselect_b64 s[18:19], -1, 0
	v_cndmask_b32_e64 v119, v115, v114, s[18:19]
	v_mul_f32_e32 v119, v119, v120
	v_cvt_pk_bf16_f32 v119, v119, v119
	ds_write_b16 v117, v119 offset:32256
	s_waitcnt lgkmcnt(9)
	s_add_i32 s15, s12, 231
	s_cmp_lt_u32 s15, 128
	s_cselect_b64 s[18:19], -1, 0
	v_cndmask_b32_e64 v119, v115, v114, s[18:19]
	v_mul_f32_e32 v119, v119, v121
	v_cvt_pk_bf16_f32 v119, v119, v119
	ds_write_b16 v117, v119 offset:33264
	s_waitcnt lgkmcnt(8)
	s_add_i32 s15, s12, 238
	s_cmp_lt_u32 s15, 128
	s_cselect_b64 s[18:19], -1, 0
	v_cndmask_b32_e64 v119, v115, v114, s[18:19]
	v_mul_f32_e32 v119, v119, v122
	v_cvt_pk_bf16_f32 v119, v119, v119
	ds_write_b16 v117, v119 offset:34272
	s_waitcnt lgkmcnt(7)
	s_add_i32 s15, s12, 245
	s_cmp_lt_u32 s15, 128
	s_cselect_b64 s[18:19], -1, 0
	v_cndmask_b32_e64 v119, v115, v114, s[18:19]
	v_mul_f32_e32 v119, v119, v123
	v_cvt_pk_bf16_f32 v119, v119, v119
	ds_write_b16 v117, v119 offset:35280
	s_cmp_gt_u32 s12, 3
	s_cbranch_scc1 .Lrhs_done
	s_mov_b32 s14, 0xc9f0
	v_add_u32_e32 v118, s14, v116
	ds_read_b32 v120, v118
	s_waitcnt lgkmcnt(0)
	v_mul_f32_e32 v119, v115, v120
	v_cvt_pk_bf16_f32 v119, v119, v119
	ds_write_b16 v117, v119 offset:36288
; __device__ void dn_pre_item(const Params& p, int L, int idx) {
;     ...
;   if (wid == 0) {
;     const int blk = lane >> 5, j = lane & 31;
;     const float* Ab = As + (blk * 32) * 65 + blk * 32;
;     float x[32];
; #pragma unroll
;     for (int c = 0; c < 32; ++c) {
;       float r = (c == j) ? 1.0f : 0.0f;
; #pragma unroll
;       for (int s = 0; s < c; ++s) r -= Ab[c * 65 + s] * x[s];
;       x[c] = r;
;     }
; #pragma unroll
;     for (int c = 0; c < 32; ++c) Tf[(blk * 32 + c) * 65 + blk * 32 + j] = x[c];
;   } else {
;     for (int e = tid - 64; e < 16384; e += 448) {
;       const int col = e >> 6, s = e & 63;
;       float v = (col < 128) ? betas[s] * vs[s * 132 + col] : betas[s] * egc[s] * ks[s * 132 + (col - 128)];
;       rhsT[col * 72 + s] = f2bf(v);
;     }
.Lrhs_done:
.LBB0_569:
	s_andn2_saveexec_b64 s[0:1], s[0:1]
	s_cbranch_execz .LBB0_571
	v_and_b32_e32 v112, 32, v40
	v_and_b32_e32 v113, 31, v40
	s_movk_i32 s2, 0x108
	v_mad_u32_u24 v114, v112, s2, v20
	v_mov_b32_e32 v115, v114
	v_lshl_add_u32 v116, v113, 2, v114
	v_add_u32_e32 v115, 260, v115
	ds_read2_b32 v[152:153], v115 offset0:0 offset1:1
	v_add_u32_e32 v115, 260, v115
	ds_read2_b32 v[154:155], v115 offset0:0 offset1:1
	v_add_u32_e32 v115, 260, v115
	ds_read2_b32 v[156:157], v115 offset0:0 offset1:1
	ds_read2_b32 v[158:159], v115 offset0:2 offset1:3
	v_add_u32_e32 v115, 260, v115
	ds_read2_b32 v[160:161], v115 offset0:0 offset1:1
	ds_read2_b32 v[162:163], v115 offset0:2 offset1:3
	v_add_u32_e32 v115, 260, v115
	ds_read2_b32 v[164:165], v115 offset0:0 offset1:1
	ds_read2_b32 v[166:167], v115 offset0:2 offset1:3
	ds_read2_b32 v[168:169], v115 offset0:4 offset1:5
	v_add_u32_e32 v115, 260, v115
	ds_read2_b32 v[170:171], v115 offset0:0 offset1:1
	ds_read2_b32 v[172:173], v115 offset0:2 offset1:3
	ds_read2_b32 v[174:175], v115 offset0:4 offset1:5
	v_cmp_eq_u32_e32 vcc, 0, v113
	v_cmp_eq_u32_e64 s[2:3], 1, v113
	s_nop 0
	v_cndmask_b32_e64 v120, 0, 1.0, vcc
	v_cndmask_b32_e64 v121, 0, 1.0, s[2:3]
	v_cmp_eq_u32_e32 vcc, 2, v113
	v_cmp_eq_u32_e64 s[2:3], 3, v113
	s_nop 0
	v_cndmask_b32_e64 v122, 0, 1.0, vcc
	v_cndmask_b32_e64 v123, 0, 1.0, s[2:3]
	v_cmp_eq_u32_e32 vcc, 4, v113
	v_cmp_eq_u32_e64 s[2:3], 5, v113
	s_nop 0
	v_cndmask_b32_e64 v124, 0, 1.0, vcc
	v_cndmask_b32_e64 v125, 0, 1.0, s[2:3]
	v_cmp_eq_u32_e32 vcc, 6, v113
	v_cmp_eq_u32_e64 s[2:3], 7, v113
	s_nop 0
	v_cndmask_b32_e64 v126, 0, 1.0, vcc
	v_cndmask_b32_e64 v127, 0, 1.0, s[2:3]
	v_cmp_eq_u32_e32 vcc, 8, v113
	v_cmp_eq_u32_e64 s[2:3], 9, v113
	s_nop 0
	v_cndmask_b32_e64 v128, 0, 1.0, vcc
	v_cndmask_b32_e64 v129, 0, 1.0, s[2:3]
	v_cmp_eq_u32_e32 vcc, 10, v113
	v_cmp_eq_u32_e64 s[2:3], 11, v113
	s_nop 0
	v_cndmask_b32_e64 v130, 0, 1.0, vcc
	v_cndmask_b32_e64 v131, 0, 1.0, s[2:3]
	v_cmp_eq_u32_e32 vcc, 12, v113
	v_cmp_eq_u32_e64 s[2:3], 13, v113
	s_nop 0
	v_cndmask_b32_e64 v132, 0, 1.0, vcc
	v_cndmask_b32_e64 v133, 0, 1.0, s[2:3]
	v_cmp_eq_u32_e32 vcc, 14, v113
	v_cmp_eq_u32_e64 s[2:3], 15, v113
	s_nop 0
	v_cndmask_b32_e64 v134, 0, 1.0, vcc
	v_cndmask_b32_e64 v135, 0, 1.0, s[2:3]
	v_cmp_eq_u32_e32 vcc, 16, v113
	v_cmp_eq_u32_e64 s[2:3], 17, v113
	s_nop 0
	v_cndmask_b32_e64 v136, 0, 1.0, vcc
	v_cndmask_b32_e64 v137, 0, 1.0, s[2:3]
	v_cmp_eq_u32_e32 vcc, 18, v113
	v_cmp_eq_u32_e64 s[2:3], 19, v113
	s_nop 0
	v_cndmask_b32_e64 v138, 0, 1.0, vcc
	v_cndmask_b32_e64 v139, 0, 1.0, s[2:3]
	v_cmp_eq_u32_e32 vcc, 20, v113
	v_cmp_eq_u32_e64 s[2:3], 21, v113
	s_nop 0
	v_cndmask_b32_e64 v140, 0, 1.0, vcc
	v_cndmask_b32_e64 v141, 0, 1.0, s[2:3]
	v_cmp_eq_u32_e32 vcc, 22, v113
	v_cmp_eq_u32_e64 s[2:3], 23, v113
	s_nop 0
	v_cndmask_b32_e64 v142, 0, 1.0, vcc
	v_cndmask_b32_e64 v143, 0, 1.0, s[2:3]
	v_cmp_eq_u32_e32 vcc, 24, v113
	v_cmp_eq_u32_e64 s[2:3], 25, v113
	s_nop 0
	v_cndmask_b32_e64 v144, 0, 1.0, vcc
	v_cndmask_b32_e64 v145, 0, 1.0, s[2:3]
	v_cmp_eq_u32_e32 vcc, 26, v113
	v_cmp_eq_u32_e64 s[2:3], 27, v113
	s_nop 0
	v_cndmask_b32_e64 v146, 0, 1.0, vcc
	v_cndmask_b32_e64 v147, 0, 1.0, s[2:3]
	v_cmp_eq_u32_e32 vcc, 28, v113
	v_cmp_eq_u32_e64 s[2:3], 29, v113
	s_nop 0
	v_cndmask_b32_e64 v148, 0, 1.0, vcc
	v_cndmask_b32_e64 v149, 0, 1.0, s[2:3]
	v_cmp_eq_u32_e32 vcc, 30, v113
	v_cmp_eq_u32_e64 s[2:3], 31, v113
	s_nop 0
	v_cndmask_b32_e64 v150, 0, 1.0, vcc
	v_cndmask_b32_e64 v151, 0, 1.0, s[2:3]
	v_add_u32_e32 v115, 260, v115
	ds_read2_b32 v[176:177], v115 offset0:0 offset1:1
	s_waitcnt lgkmcnt(12)
	v_fma_f32 v121, -v152, v120, v121
	ds_read2_b32 v[152:153], v115 offset0:2 offset1:3
	s_waitcnt lgkmcnt(12)
	v_fma_f32 v122, -v154, v120, v122
	v_fma_f32 v122, -v155, v121, v122
	ds_read2_b32 v[154:155], v115 offset0:4 offset1:5
	s_waitcnt lgkmcnt(12)
	v_fma_f32 v123, -v156, v120, v123
	v_fma_f32 v123, -v157, v121, v123
	ds_read2_b32 v[156:157], v115 offset0:6 offset1:7
	s_waitcnt lgkmcnt(12)
	v_fma_f32 v123, -v158, v122, v123
	v_add_u32_e32 v115, 260, v115
	ds_read2_b32 v[158:159], v115 offset0:0 offset1:1
	s_waitcnt lgkmcnt(12)
	v_fma_f32 v124, -v160, v120, v124
	v_fma_f32 v124, -v161, v121, v124
	ds_read2_b32 v[160:161], v115 offset0:2 offset1:3
	s_waitcnt lgkmcnt(12)
	v_fma_f32 v124, -v162, v122, v124
	v_fma_f32 v124, -v163, v123, v124
	ds_read2_b32 v[162:163], v115 offset0:4 offset1:5
	s_waitcnt lgkmcnt(12)
	v_fma_f32 v125, -v164, v120, v125
	v_fma_f32 v125, -v165, v121, v125
	ds_read2_b32 v[164:165], v115 offset0:6 offset1:7
	s_waitcnt lgkmcnt(12)
	v_fma_f32 v125, -v166, v122, v125
	v_fma_f32 v125, -v167, v123, v125
	v_add_u32_e32 v115, 260, v115
	ds_read2_b32 v[166:167], v115 offset0:0 offset1:1
	s_waitcnt lgkmcnt(12)
	v_fma_f32 v125, -v168, v124, v125
	ds_read2_b32 v[168:169], v115 offset0:2 offset1:3
	s_waitcnt lgkmcnt(12)
	v_fma_f32 v126, -v170, v120, v126
	v_fma_f32 v126, -v171, v121, v126
	ds_read2_b32 v[170:171], v115 offset0:4 offset1:5
	s_waitcnt lgkmcnt(12)
	v_fma_f32 v126, -v172, v122, v126
	v_fma_f32 v126, -v173, v123, v126
	ds_read2_b32 v[172:173], v115 offset0:6 offset1:7
	s_waitcnt lgkmcnt(12)
	v_fma_f32 v126, -v174, v124, v126
	v_fma_f32 v126, -v175, v125, v126
	ds_read2_b32 v[174:175], v115 offset0:8 offset1:9
	s_waitcnt lgkmcnt(12)
	v_fma_f32 v127, -v176, v120, v127
	v_fma_f32 v127, -v177, v121, v127
	v_add_u32_e32 v115, 260, v115
	ds_read2_b32 v[176:177], v115 offset0:0 offset1:1
	s_waitcnt lgkmcnt(12)
	v_fma_f32 v127, -v152, v122, v127
	v_fma_f32 v127, -v153, v123, v127
	ds_read2_b32 v[152:153], v115 offset0:2 offset1:3
	s_waitcnt lgkmcnt(12)
; __device__ void dn_pre_item(const Params& p, int L, int idx) {
;     ...
;   if (wid == 0) {
;     const int blk = lane >> 5, j = lane & 31;
;     const float* Ab = As + (blk * 32) * 65 + blk * 32;
;     float x[32];
; #pragma unroll
;     for (int c = 0; c < 32; ++c) {
;       float r = (c == j) ? 1.0f : 0.0f;
; #pragma unroll
;       for (int s = 0; s < c; ++s) r -= Ab[c * 65 + s] * x[s];
;       x[c] = r;
;     }
	v_fma_f32 v127, -v154, v124, v127
	v_fma_f32 v127, -v155, v125, v127
	ds_read2_b32 v[154:155], v115 offset0:4 offset1:5
	s_waitcnt lgkmcnt(12)
	v_fma_f32 v127, -v156, v126, v127
	ds_read2_b32 v[156:157], v115 offset0:6 offset1:7
	s_waitcnt lgkmcnt(12)
	v_fma_f32 v128, -v158, v120, v128
	v_fma_f32 v128, -v159, v121, v128
	ds_read2_b32 v[158:159], v115 offset0:8 offset1:9
	s_waitcnt lgkmcnt(12)
	v_fma_f32 v128, -v160, v122, v128
	v_fma_f32 v128, -v161, v123, v128
	v_add_u32_e32 v115, 260, v115
	ds_read2_b32 v[160:161], v115 offset0:0 offset1:1
	s_waitcnt lgkmcnt(12)
	v_fma_f32 v128, -v162, v124, v128
	v_fma_f32 v128, -v163, v125, v128
	ds_read2_b32 v[162:163], v115 offset0:2 offset1:3
	s_waitcnt lgkmcnt(12)
	v_fma_f32 v128, -v164, v126, v128
	v_fma_f32 v128, -v165, v127, v128
	ds_read2_b32 v[164:165], v115 offset0:4 offset1:5
	s_waitcnt lgkmcnt(12)
	v_fma_f32 v129, -v166, v120, v129
	v_fma_f32 v129, -v167, v121, v129
	ds_read2_b32 v[166:167], v115 offset0:6 offset1:7
	s_waitcnt lgkmcnt(12)
	v_fma_f32 v129, -v168, v122, v129
	v_fma_f32 v129, -v169, v123, v129
	ds_read2_b32 v[168:169], v115 offset0:8 offset1:9
	s_waitcnt lgkmcnt(12)
	v_fma_f32 v129, -v170, v124, v129
	v_fma_f32 v129, -v171, v125, v129
	ds_read2_b32 v[170:171], v115 offset0:10 offset1:11
	s_waitcnt lgkmcnt(12)
	v_fma_f32 v129, -v172, v126, v129
	v_fma_f32 v129, -v173, v127, v129
	v_add_u32_e32 v115, 260, v115
	ds_read2_b32 v[172:173], v115 offset0:0 offset1:1
	s_waitcnt lgkmcnt(12)
	v_fma_f32 v129, -v174, v128, v129
	ds_read2_b32 v[174:175], v115 offset0:2 offset1:3
	s_waitcnt lgkmcnt(12)
	v_fma_f32 v130, -v176, v120, v130
	v_fma_f32 v130, -v177, v121, v130
	ds_read2_b32 v[176:177], v115 offset0:4 offset1:5
	s_waitcnt lgkmcnt(12)
	v_fma_f32 v130, -v152, v122, v130
	v_fma_f32 v130, -v153, v123, v130
	ds_read2_b32 v[152:153], v115 offset0:6 offset1:7
	s_waitcnt lgkmcnt(12)
	v_fma_f32 v130, -v154, v124, v130
	v_fma_f32 v130, -v155, v125, v130
	ds_read2_b32 v[154:155], v115 offset0:8 offset1:9
	s_waitcnt lgkmcnt(12)
	v_fma_f32 v130, -v156, v126, v130
	v_fma_f32 v130, -v157, v127, v130
	ds_read2_b32 v[156:157], v115 offset0:10 offset1:11
	s_waitcnt lgkmcnt(12)
	v_fma_f32 v130, -v158, v128, v130
	v_fma_f32 v130, -v159, v129, v130
	v_add_u32_e32 v115, 260, v115
	ds_read2_b32 v[158:159], v115 offset0:0 offset1:1
	s_waitcnt lgkmcnt(12)
	v_fma_f32 v131, -v160, v120, v131
	v_fma_f32 v131, -v161, v121, v131
	ds_read2_b32 v[160:161], v115 offset0:2 offset1:3
	s_waitcnt lgkmcnt(12)
	v_fma_f32 v131, -v162, v122, v131
	v_fma_f32 v131, -v163, v123, v131
	ds_read2_b32 v[162:163], v115 offset0:4 offset1:5
	s_waitcnt lgkmcnt(12)
	v_fma_f32 v131, -v164, v124, v131
	v_fma_f32 v131, -v165, v125, v131
	ds_read2_b32 v[164:165], v115 offset0:6 offset1:7
	s_waitcnt lgkmcnt(12)
	v_fma_f32 v131, -v166, v126, v131
	v_fma_f32 v131, -v167, v127, v131
	ds_read2_b32 v[166:167], v115 offset0:8 offset1:9
	s_waitcnt lgkmcnt(12)
	v_fma_f32 v131, -v168, v128, v131
	v_fma_f32 v131, -v169, v129, v131
	ds_read2_b32 v[168:169], v115 offset0:10 offset1:11
	s_waitcnt lgkmcnt(12)
	v_fma_f32 v131, -v170, v130, v131
	ds_read2_b32 v[170:171], v115 offset0:12 offset1:13
	s_waitcnt lgkmcnt(12)
	v_fma_f32 v132, -v172, v120, v132
	v_fma_f32 v132, -v173, v121, v132
	v_add_u32_e32 v115, 260, v115
	ds_read2_b32 v[172:173], v115 offset0:0 offset1:1
	s_waitcnt lgkmcnt(12)
	v_fma_f32 v132, -v174, v122, v132
	v_fma_f32 v132, -v175, v123, v132
	ds_read2_b32 v[174:175], v115 offset0:2 offset1:3
	s_waitcnt lgkmcnt(12)
	v_fma_f32 v132, -v176, v124, v132
	v_fma_f32 v132, -v177, v125, v132
	ds_read2_b32 v[176:177], v115 offset0:4 offset1:5
	s_waitcnt lgkmcnt(12)
	v_fma_f32 v132, -v152, v126, v132
	v_fma_f32 v132, -v153, v127, v132
	ds_read2_b32 v[152:153], v115 offset0:6 offset1:7
	s_waitcnt lgkmcnt(12)
	v_fma_f32 v132, -v154, v128, v132
	v_fma_f32 v132, -v155, v129, v132
	ds_read2_b32 v[154:155], v115 offset0:8 offset1:9
	s_waitcnt lgkmcnt(12)
	v_fma_f32 v132, -v156, v130, v132
	v_fma_f32 v132, -v157, v131, v132
	ds_read2_b32 v[156:157], v115 offset0:10 offset1:11
	s_waitcnt lgkmcnt(12)
	v_fma_f32 v133, -v158, v120, v133
	v_fma_f32 v133, -v159, v121, v133
	ds_read2_b32 v[158:159], v115 offset0:12 offset1:13
	s_waitcnt lgkmcnt(12)
	v_fma_f32 v133, -v160, v122, v133
	v_fma_f32 v133, -v161, v123, v133
	v_add_u32_e32 v115, 260, v115
	ds_read2_b32 v[160:161], v115 offset0:0 offset1:1
	s_waitcnt lgkmcnt(12)
	v_fma_f32 v133, -v162, v124, v133
	v_fma_f32 v133, -v163, v125, v133
	ds_read2_b32 v[162:163], v115 offset0:2 offset1:3
	s_waitcnt lgkmcnt(12)
	v_fma_f32 v133, -v164, v126, v133
	v_fma_f32 v133, -v165, v127, v133
	ds_read2_b32 v[164:165], v115 offset0:4 offset1:5
	s_waitcnt lgkmcnt(12)
	v_fma_f32 v133, -v166, v128, v133
	v_fma_f32 v133, -v167, v129, v133
	ds_read2_b32 v[166:167], v115 offset0:6 offset1:7
	s_waitcnt lgkmcnt(12)
	v_fma_f32 v133, -v168, v130, v133
	v_fma_f32 v133, -v169, v131, v133
	ds_read2_b32 v[168:169], v115 offset0:8 offset1:9
	s_waitcnt lgkmcnt(12)
	v_fma_f32 v133, -v170, v132, v133
	ds_read2_b32 v[170:171], v115 offset0:10 offset1:11
	s_waitcnt lgkmcnt(12)
	v_fma_f32 v134, -v172, v120, v134
	v_fma_f32 v134, -v173, v121, v134
	ds_read2_b32 v[172:173], v115 offset0:12 offset1:13
	s_waitcnt lgkmcnt(12)
	v_fma_f32 v134, -v174, v122, v134
	v_fma_f32 v134, -v175, v123, v134
	ds_read2_b32 v[174:175], v115 offset0:14 offset1:15
	s_waitcnt lgkmcnt(12)
	v_fma_f32 v134, -v176, v124, v134
	v_fma_f32 v134, -v177, v125, v134
	v_add_u32_e32 v115, 260, v115
	ds_read2_b32 v[176:177], v115 offset0:0 offset1:1
	s_waitcnt lgkmcnt(12)
	v_fma_f32 v134, -v152, v126, v134
	v_fma_f32 v134, -v153, v127, v134
	ds_read2_b32 v[152:153], v115 offset0:2 offset1:3
	s_waitcnt lgkmcnt(12)
; __device__ void dn_pre_item(const Params& p, int L, int idx) {
;     ...
;   if (wid == 0) {
;     const int blk = lane >> 5, j = lane & 31;
;     const float* Ab = As + (blk * 32) * 65 + blk * 32;
;     float x[32];
; #pragma unroll
;     for (int c = 0; c < 32; ++c) {
;       float r = (c == j) ? 1.0f : 0.0f;
; #pragma unroll
;       for (int s = 0; s < c; ++s) r -= Ab[c * 65 + s] * x[s];
;       x[c] = r;
;     }
	v_fma_f32 v134, -v154, v128, v134
	v_fma_f32 v134, -v155, v129, v134
	ds_read2_b32 v[154:155], v115 offset0:4 offset1:5
	s_waitcnt lgkmcnt(12)
	v_fma_f32 v134, -v156, v130, v134
	v_fma_f32 v134, -v157, v131, v134
	ds_read2_b32 v[156:157], v115 offset0:6 offset1:7
	s_waitcnt lgkmcnt(12)
	v_fma_f32 v134, -v158, v132, v134
	v_fma_f32 v134, -v159, v133, v134
	ds_read2_b32 v[158:159], v115 offset0:8 offset1:9
	s_waitcnt lgkmcnt(12)
	v_fma_f32 v135, -v160, v120, v135
	v_fma_f32 v135, -v161, v121, v135
	ds_read2_b32 v[160:161], v115 offset0:10 offset1:11
	s_waitcnt lgkmcnt(12)
	v_fma_f32 v135, -v162, v122, v135
	v_fma_f32 v135, -v163, v123, v135
	ds_read2_b32 v[162:163], v115 offset0:12 offset1:13
	s_waitcnt lgkmcnt(12)
	v_fma_f32 v135, -v164, v124, v135
	v_fma_f32 v135, -v165, v125, v135
	ds_read2_b32 v[164:165], v115 offset0:14 offset1:15
	s_waitcnt lgkmcnt(12)
	v_fma_f32 v135, -v166, v126, v135
	v_fma_f32 v135, -v167, v127, v135
	v_add_u32_e32 v115, 260, v115
	ds_read2_b32 v[166:167], v115 offset0:0 offset1:1
	s_waitcnt lgkmcnt(12)
	v_fma_f32 v135, -v168, v128, v135
	v_fma_f32 v135, -v169, v129, v135
	ds_read2_b32 v[168:169], v115 offset0:2 offset1:3
	s_waitcnt lgkmcnt(12)
	v_fma_f32 v135, -v170, v130, v135
	v_fma_f32 v135, -v171, v131, v135
	ds_read2_b32 v[170:171], v115 offset0:4 offset1:5
	s_waitcnt lgkmcnt(12)
	v_fma_f32 v135, -v172, v132, v135
	v_fma_f32 v135, -v173, v133, v135
	ds_read2_b32 v[172:173], v115 offset0:6 offset1:7
	s_waitcnt lgkmcnt(12)
	v_fma_f32 v135, -v174, v134, v135
	ds_read2_b32 v[174:175], v115 offset0:8 offset1:9
	s_waitcnt lgkmcnt(12)
	v_fma_f32 v136, -v176, v120, v136
	v_fma_f32 v136, -v177, v121, v136
	ds_read2_b32 v[176:177], v115 offset0:10 offset1:11
	s_waitcnt lgkmcnt(12)
	v_fma_f32 v136, -v152, v122, v136
	v_fma_f32 v136, -v153, v123, v136
	ds_read2_b32 v[152:153], v115 offset0:12 offset1:13
	s_waitcnt lgkmcnt(12)
	v_fma_f32 v136, -v154, v124, v136
	v_fma_f32 v136, -v155, v125, v136
	ds_read2_b32 v[154:155], v115 offset0:14 offset1:15
	s_waitcnt lgkmcnt(12)
	v_fma_f32 v136, -v156, v126, v136
	v_fma_f32 v136, -v157, v127, v136
	ds_read2_b32 v[156:157], v115 offset0:16 offset1:17
	s_waitcnt lgkmcnt(12)
	v_fma_f32 v136, -v158, v128, v136
	v_fma_f32 v136, -v159, v129, v136
	v_add_u32_e32 v115, 260, v115
	ds_read2_b32 v[158:159], v115 offset0:0 offset1:1
	s_waitcnt lgkmcnt(12)
	v_fma_f32 v136, -v160, v130, v136
	v_fma_f32 v136, -v161, v131, v136
	ds_read2_b32 v[160:161], v115 offset0:2 offset1:3
	s_waitcnt lgkmcnt(12)
	v_fma_f32 v136, -v162, v132, v136
	v_fma_f32 v136, -v163, v133, v136
	ds_read2_b32 v[162:163], v115 offset0:4 offset1:5
	s_waitcnt lgkmcnt(12)
	v_fma_f32 v136, -v164, v134, v136
	v_fma_f32 v136, -v165, v135, v136
	ds_read2_b32 v[164:165], v115 offset0:6 offset1:7
	s_waitcnt lgkmcnt(12)
	v_fma_f32 v137, -v166, v120, v137
	v_fma_f32 v137, -v167, v121, v137
	ds_read2_b32 v[166:167], v115 offset0:8 offset1:9
	s_waitcnt lgkmcnt(12)
	v_fma_f32 v137, -v168, v122, v137
	v_fma_f32 v137, -v169, v123, v137
	ds_read2_b32 v[168:169], v115 offset0:10 offset1:11
	s_waitcnt lgkmcnt(12)
	v_fma_f32 v137, -v170, v124, v137
	v_fma_f32 v137, -v171, v125, v137
	ds_read2_b32 v[170:171], v115 offset0:12 offset1:13
	s_waitcnt lgkmcnt(12)
	v_fma_f32 v137, -v172, v126, v137
	v_fma_f32 v137, -v173, v127, v137
	ds_read2_b32 v[172:173], v115 offset0:14 offset1:15
	s_waitcnt lgkmcnt(12)
	v_fma_f32 v137, -v174, v128, v137
	v_fma_f32 v137, -v175, v129, v137
	ds_read2_b32 v[174:175], v115 offset0:16 offset1:17
	s_waitcnt lgkmcnt(12)
	v_fma_f32 v137, -v176, v130, v137
	v_fma_f32 v137, -v177, v131, v137
	v_add_u32_e32 v115, 260, v115
	ds_read2_b32 v[176:177], v115 offset0:0 offset1:1
	s_waitcnt lgkmcnt(12)
	v_fma_f32 v137, -v152, v132, v137
	v_fma_f32 v137, -v153, v133, v137
	ds_read2_b32 v[152:153], v115 offset0:2 offset1:3
	s_waitcnt lgkmcnt(12)
	v_fma_f32 v137, -v154, v134, v137
	v_fma_f32 v137, -v155, v135, v137
	ds_read2_b32 v[154:155], v115 offset0:4 offset1:5
	s_waitcnt lgkmcnt(12)
	v_fma_f32 v137, -v156, v136, v137
	ds_read2_b32 v[156:157], v115 offset0:6 offset1:7
	s_waitcnt lgkmcnt(12)
	v_fma_f32 v138, -v158, v120, v138
	v_fma_f32 v138, -v159, v121, v138
	ds_read2_b32 v[158:159], v115 offset0:8 offset1:9
	s_waitcnt lgkmcnt(12)
	v_fma_f32 v138, -v160, v122, v138
	v_fma_f32 v138, -v161, v123, v138
	ds_read2_b32 v[160:161], v115 offset0:10 offset1:11
	s_waitcnt lgkmcnt(12)
	v_fma_f32 v138, -v162, v124, v138
	v_fma_f32 v138, -v163, v125, v138
	ds_read2_b32 v[162:163], v115 offset0:12 offset1:13
	s_waitcnt lgkmcnt(12)
	v_fma_f32 v138, -v164, v126, v138
	v_fma_f32 v138, -v165, v127, v138
	ds_read2_b32 v[164:165], v115 offset0:14 offset1:15
	s_waitcnt lgkmcnt(12)
	v_fma_f32 v138, -v166, v128, v138
	v_fma_f32 v138, -v167, v129, v138
	ds_read2_b32 v[166:167], v115 offset0:16 offset1:17
	s_waitcnt lgkmcnt(12)
	v_fma_f32 v138, -v168, v130, v138
	v_fma_f32 v138, -v169, v131, v138
	ds_read2_b32 v[168:169], v115 offset0:18 offset1:19
	s_waitcnt lgkmcnt(12)
	v_fma_f32 v138, -v170, v132, v138
	v_fma_f32 v138, -v171, v133, v138
	v_add_u32_e32 v115, 260, v115
	ds_read2_b32 v[170:171], v115 offset0:0 offset1:1
	s_waitcnt lgkmcnt(12)
	v_fma_f32 v138, -v172, v134, v138
	v_fma_f32 v138, -v173, v135, v138
	ds_read2_b32 v[172:173], v115 offset0:2 offset1:3
	s_waitcnt lgkmcnt(12)
	v_fma_f32 v138, -v174, v136, v138
	v_fma_f32 v138, -v175, v137, v138
	ds_read2_b32 v[174:175], v115 offset0:4 offset1:5
	s_waitcnt lgkmcnt(12)
	v_fma_f32 v139, -v176, v120, v139
	v_fma_f32 v139, -v177, v121, v139
	ds_read2_b32 v[176:177], v115 offset0:6 offset1:7
	s_waitcnt lgkmcnt(12)
	v_fma_f32 v139, -v152, v122, v139
	v_fma_f32 v139, -v153, v123, v139
	ds_read2_b32 v[152:153], v115 offset0:8 offset1:9
	s_waitcnt lgkmcnt(12)
; __device__ void dn_pre_item(const Params& p, int L, int idx) {
;     ...
;   if (wid == 0) {
;     const int blk = lane >> 5, j = lane & 31;
;     const float* Ab = As + (blk * 32) * 65 + blk * 32;
;     float x[32];
; #pragma unroll
;     for (int c = 0; c < 32; ++c) {
;       float r = (c == j) ? 1.0f : 0.0f;
; #pragma unroll
;       for (int s = 0; s < c; ++s) r -= Ab[c * 65 + s] * x[s];
;       x[c] = r;
;     }
	v_fma_f32 v139, -v154, v124, v139
	v_fma_f32 v139, -v155, v125, v139
	ds_read2_b32 v[154:155], v115 offset0:10 offset1:11
	s_waitcnt lgkmcnt(12)
	v_fma_f32 v139, -v156, v126, v139
	v_fma_f32 v139, -v157, v127, v139
	ds_read2_b32 v[156:157], v115 offset0:12 offset1:13
	s_waitcnt lgkmcnt(12)
	v_fma_f32 v139, -v158, v128, v139
	v_fma_f32 v139, -v159, v129, v139
	ds_read2_b32 v[158:159], v115 offset0:14 offset1:15
	s_waitcnt lgkmcnt(12)
	v_fma_f32 v139, -v160, v130, v139
	v_fma_f32 v139, -v161, v131, v139
	ds_read2_b32 v[160:161], v115 offset0:16 offset1:17
	s_waitcnt lgkmcnt(12)
	v_fma_f32 v139, -v162, v132, v139
	v_fma_f32 v139, -v163, v133, v139
	ds_read2_b32 v[162:163], v115 offset0:18 offset1:19
	s_waitcnt lgkmcnt(12)
	v_fma_f32 v139, -v164, v134, v139
	v_fma_f32 v139, -v165, v135, v139
	v_add_u32_e32 v115, 260, v115
	ds_read2_b32 v[164:165], v115 offset0:0 offset1:1
	s_waitcnt lgkmcnt(12)
	v_fma_f32 v139, -v166, v136, v139
	v_fma_f32 v139, -v167, v137, v139
	ds_read2_b32 v[166:167], v115 offset0:2 offset1:3
	s_waitcnt lgkmcnt(12)
	v_fma_f32 v139, -v168, v138, v139
	ds_read2_b32 v[168:169], v115 offset0:4 offset1:5
	s_waitcnt lgkmcnt(12)
	v_fma_f32 v140, -v170, v120, v140
	v_fma_f32 v140, -v171, v121, v140
	ds_read2_b32 v[170:171], v115 offset0:6 offset1:7
	s_waitcnt lgkmcnt(12)
	v_fma_f32 v140, -v172, v122, v140
	v_fma_f32 v140, -v173, v123, v140
	ds_read2_b32 v[172:173], v115 offset0:8 offset1:9
	s_waitcnt lgkmcnt(12)
	v_fma_f32 v140, -v174, v124, v140
	v_fma_f32 v140, -v175, v125, v140
	ds_read2_b32 v[174:175], v115 offset0:10 offset1:11
	s_waitcnt lgkmcnt(12)
	v_fma_f32 v140, -v176, v126, v140
	v_fma_f32 v140, -v177, v127, v140
	ds_read2_b32 v[176:177], v115 offset0:12 offset1:13
	s_waitcnt lgkmcnt(12)
	v_fma_f32 v140, -v152, v128, v140
	v_fma_f32 v140, -v153, v129, v140
	ds_read2_b32 v[152:153], v115 offset0:14 offset1:15
	s_waitcnt lgkmcnt(12)
	v_fma_f32 v140, -v154, v130, v140
	v_fma_f32 v140, -v155, v131, v140
	ds_read2_b32 v[154:155], v115 offset0:16 offset1:17
	s_waitcnt lgkmcnt(12)
	v_fma_f32 v140, -v156, v132, v140
	v_fma_f32 v140, -v157, v133, v140
	ds_read2_b32 v[156:157], v115 offset0:18 offset1:19
	s_waitcnt lgkmcnt(12)
	v_fma_f32 v140, -v158, v134, v140
	v_fma_f32 v140, -v159, v135, v140
	ds_read2_b32 v[158:159], v115 offset0:20 offset1:21
	s_waitcnt lgkmcnt(12)
	v_fma_f32 v140, -v160, v136, v140
	v_fma_f32 v140, -v161, v137, v140
	v_add_u32_e32 v115, 260, v115
	ds_read2_b32 v[160:161], v115 offset0:0 offset1:1
	s_waitcnt lgkmcnt(12)
	v_fma_f32 v140, -v162, v138, v140
	v_fma_f32 v140, -v163, v139, v140
	ds_read2_b32 v[162:163], v115 offset0:2 offset1:3
	s_waitcnt lgkmcnt(12)
	v_fma_f32 v141, -v164, v120, v141
	v_fma_f32 v141, -v165, v121, v141
	ds_read2_b32 v[164:165], v115 offset0:4 offset1:5
	s_waitcnt lgkmcnt(12)
	v_fma_f32 v141, -v166, v122, v141
	v_fma_f32 v141, -v167, v123, v141
	ds_read2_b32 v[166:167], v115 offset0:6 offset1:7
	s_waitcnt lgkmcnt(12)
	v_fma_f32 v141, -v168, v124, v141
	v_fma_f32 v141, -v169, v125, v141
	ds_read2_b32 v[168:169], v115 offset0:8 offset1:9
	s_waitcnt lgkmcnt(12)
	v_fma_f32 v141, -v170, v126, v141
	v_fma_f32 v141, -v171, v127, v141
	ds_read2_b32 v[170:171], v115 offset0:10 offset1:11
	s_waitcnt lgkmcnt(12)
	v_fma_f32 v141, -v172, v128, v141
	v_fma_f32 v141, -v173, v129, v141
	ds_read2_b32 v[172:173], v115 offset0:12 offset1:13
	s_waitcnt lgkmcnt(12)
	v_fma_f32 v141, -v174, v130, v141
	v_fma_f32 v141, -v175, v131, v141
	ds_read2_b32 v[174:175], v115 offset0:14 offset1:15
	s_waitcnt lgkmcnt(12)
	v_fma_f32 v141, -v176, v132, v141
	v_fma_f32 v141, -v177, v133, v141
	ds_read2_b32 v[176:177], v115 offset0:16 offset1:17
	s_waitcnt lgkmcnt(12)
	v_fma_f32 v141, -v152, v134, v141
	v_fma_f32 v141, -v153, v135, v141
	ds_read2_b32 v[152:153], v115 offset0:18 offset1:19
	s_waitcnt lgkmcnt(12)
	v_fma_f32 v141, -v154, v136, v141
	v_fma_f32 v141, -v155, v137, v141
	ds_read2_b32 v[154:155], v115 offset0:20 offset1:21
	s_waitcnt lgkmcnt(12)
	v_fma_f32 v141, -v156, v138, v141
	v_fma_f32 v141, -v157, v139, v141
	v_add_u32_e32 v115, 260, v115
	ds_read2_b32 v[156:157], v115 offset0:0 offset1:1
	s_waitcnt lgkmcnt(12)
	v_fma_f32 v141, -v158, v140, v141
	ds_read2_b32 v[158:159], v115 offset0:2 offset1:3
	s_waitcnt lgkmcnt(12)
	v_fma_f32 v142, -v160, v120, v142
	v_fma_f32 v142, -v161, v121, v142
	ds_read2_b32 v[160:161], v115 offset0:4 offset1:5
	s_waitcnt lgkmcnt(12)
	v_fma_f32 v142, -v162, v122, v142
	v_fma_f32 v142, -v163, v123, v142
	ds_read2_b32 v[162:163], v115 offset0:6 offset1:7
	s_waitcnt lgkmcnt(12)
	v_fma_f32 v142, -v164, v124, v142
	v_fma_f32 v142, -v165, v125, v142
	ds_read2_b32 v[164:165], v115 offset0:8 offset1:9
	s_waitcnt lgkmcnt(12)
	v_fma_f32 v142, -v166, v126, v142
	v_fma_f32 v142, -v167, v127, v142
	ds_read2_b32 v[166:167], v115 offset0:10 offset1:11
	s_waitcnt lgkmcnt(12)
	v_fma_f32 v142, -v168, v128, v142
	v_fma_f32 v142, -v169, v129, v142
	ds_read2_b32 v[168:169], v115 offset0:12 offset1:13
	s_waitcnt lgkmcnt(12)
	v_fma_f32 v142, -v170, v130, v142
	v_fma_f32 v142, -v171, v131, v142
	ds_read2_b32 v[170:171], v115 offset0:14 offset1:15
	s_waitcnt lgkmcnt(12)
	v_fma_f32 v142, -v172, v132, v142
	v_fma_f32 v142, -v173, v133, v142
	ds_read2_b32 v[172:173], v115 offset0:16 offset1:17
	s_waitcnt lgkmcnt(12)
	v_fma_f32 v142, -v174, v134, v142
	v_fma_f32 v142, -v175, v135, v142
	ds_read2_b32 v[174:175], v115 offset0:18 offset1:19
	s_waitcnt lgkmcnt(12)
	v_fma_f32 v142, -v176, v136, v142
	v_fma_f32 v142, -v177, v137, v142
	ds_read2_b32 v[176:177], v115 offset0:20 offset1:21
	s_waitcnt lgkmcnt(12)
	v_fma_f32 v142, -v152, v138, v142
	v_fma_f32 v142, -v153, v139, v142
	ds_read2_b32 v[152:153], v115 offset0:22 offset1:23
	s_waitcnt lgkmcnt(12)
; __device__ void dn_pre_item(const Params& p, int L, int idx) {
;     ...
;   if (wid == 0) {
;     const int blk = lane >> 5, j = lane & 31;
;     const float* Ab = As + (blk * 32) * 65 + blk * 32;
;     float x[32];
; #pragma unroll
;     for (int c = 0; c < 32; ++c) {
;       float r = (c == j) ? 1.0f : 0.0f;
; #pragma unroll
;       for (int s = 0; s < c; ++s) r -= Ab[c * 65 + s] * x[s];
;       x[c] = r;
;     }
	v_fma_f32 v142, -v154, v140, v142
	v_fma_f32 v142, -v155, v141, v142
	v_add_u32_e32 v115, 260, v115
	ds_read2_b32 v[154:155], v115 offset0:0 offset1:1
	s_waitcnt lgkmcnt(12)
	v_fma_f32 v143, -v156, v120, v143
	v_fma_f32 v143, -v157, v121, v143
	ds_read2_b32 v[156:157], v115 offset0:2 offset1:3
	s_waitcnt lgkmcnt(12)
	v_fma_f32 v143, -v158, v122, v143
	v_fma_f32 v143, -v159, v123, v143
	ds_read2_b32 v[158:159], v115 offset0:4 offset1:5
	s_waitcnt lgkmcnt(12)
	v_fma_f32 v143, -v160, v124, v143
	v_fma_f32 v143, -v161, v125, v143
	ds_read2_b32 v[160:161], v115 offset0:6 offset1:7
	s_waitcnt lgkmcnt(12)
	v_fma_f32 v143, -v162, v126, v143
	v_fma_f32 v143, -v163, v127, v143
	ds_read2_b32 v[162:163], v115 offset0:8 offset1:9
	s_waitcnt lgkmcnt(12)
	v_fma_f32 v143, -v164, v128, v143
	v_fma_f32 v143, -v165, v129, v143
	ds_read2_b32 v[164:165], v115 offset0:10 offset1:11
	s_waitcnt lgkmcnt(12)
	v_fma_f32 v143, -v166, v130, v143
	v_fma_f32 v143, -v167, v131, v143
	ds_read2_b32 v[166:167], v115 offset0:12 offset1:13
	s_waitcnt lgkmcnt(12)
	v_fma_f32 v143, -v168, v132, v143
	v_fma_f32 v143, -v169, v133, v143
	ds_read2_b32 v[168:169], v115 offset0:14 offset1:15
	s_waitcnt lgkmcnt(12)
	v_fma_f32 v143, -v170, v134, v143
	v_fma_f32 v143, -v171, v135, v143
	ds_read2_b32 v[170:171], v115 offset0:16 offset1:17
	s_waitcnt lgkmcnt(12)
	v_fma_f32 v143, -v172, v136, v143
	v_fma_f32 v143, -v173, v137, v143
	ds_read2_b32 v[172:173], v115 offset0:18 offset1:19
	s_waitcnt lgkmcnt(12)
	v_fma_f32 v143, -v174, v138, v143
	v_fma_f32 v143, -v175, v139, v143
	ds_read2_b32 v[174:175], v115 offset0:20 offset1:21
	s_waitcnt lgkmcnt(12)
	v_fma_f32 v143, -v176, v140, v143
	v_fma_f32 v143, -v177, v141, v143
	ds_read2_b32 v[176:177], v115 offset0:22 offset1:23
	s_waitcnt lgkmcnt(12)
	v_fma_f32 v143, -v152, v142, v143
	v_add_u32_e32 v115, 260, v115
	ds_read2_b32 v[152:153], v115 offset0:0 offset1:1
	s_waitcnt lgkmcnt(12)
	v_fma_f32 v144, -v154, v120, v144
	v_fma_f32 v144, -v155, v121, v144
	ds_read2_b32 v[154:155], v115 offset0:2 offset1:3
	s_waitcnt lgkmcnt(12)
	v_fma_f32 v144, -v156, v122, v144
	v_fma_f32 v144, -v157, v123, v144
	ds_read2_b32 v[156:157], v115 offset0:4 offset1:5
	s_waitcnt lgkmcnt(12)
	v_fma_f32 v144, -v158, v124, v144
	v_fma_f32 v144, -v159, v125, v144
	ds_read2_b32 v[158:159], v115 offset0:6 offset1:7
	s_waitcnt lgkmcnt(12)
	v_fma_f32 v144, -v160, v126, v144
	v_fma_f32 v144, -v161, v127, v144
	ds_read2_b32 v[160:161], v115 offset0:8 offset1:9
	s_waitcnt lgkmcnt(12)
	v_fma_f32 v144, -v162, v128, v144
	v_fma_f32 v144, -v163, v129, v144
	ds_read2_b32 v[162:163], v115 offset0:10 offset1:11
	s_waitcnt lgkmcnt(12)
	v_fma_f32 v144, -v164, v130, v144
	v_fma_f32 v144, -v165, v131, v144
	ds_read2_b32 v[164:165], v115 offset0:12 offset1:13
	s_waitcnt lgkmcnt(12)
	v_fma_f32 v144, -v166, v132, v144
	v_fma_f32 v144, -v167, v133, v144
	ds_read2_b32 v[166:167], v115 offset0:14 offset1:15
	s_waitcnt lgkmcnt(12)
	v_fma_f32 v144, -v168, v134, v144
	v_fma_f32 v144, -v169, v135, v144
	ds_read2_b32 v[168:169], v115 offset0:16 offset1:17
	s_waitcnt lgkmcnt(12)
	v_fma_f32 v144, -v170, v136, v144
	v_fma_f32 v144, -v171, v137, v144
	ds_read2_b32 v[170:171], v115 offset0:18 offset1:19
	s_waitcnt lgkmcnt(12)
	v_fma_f32 v144, -v172, v138, v144
	v_fma_f32 v144, -v173, v139, v144
	ds_read2_b32 v[172:173], v115 offset0:20 offset1:21
	s_waitcnt lgkmcnt(12)
	v_fma_f32 v144, -v174, v140, v144
	v_fma_f32 v144, -v175, v141, v144
	ds_read2_b32 v[174:175], v115 offset0:22 offset1:23
	s_waitcnt lgkmcnt(12)
	v_fma_f32 v144, -v176, v142, v144
	v_fma_f32 v144, -v177, v143, v144
	ds_read2_b32 v[176:177], v115 offset0:24 offset1:25
	s_waitcnt lgkmcnt(12)
	v_fma_f32 v145, -v152, v120, v145
	v_fma_f32 v145, -v153, v121, v145
	v_add_u32_e32 v115, 260, v115
	ds_read2_b32 v[152:153], v115 offset0:0 offset1:1
	s_waitcnt lgkmcnt(12)
	v_fma_f32 v145, -v154, v122, v145
	v_fma_f32 v145, -v155, v123, v145
	ds_read2_b32 v[154:155], v115 offset0:2 offset1:3
	s_waitcnt lgkmcnt(12)
	v_fma_f32 v145, -v156, v124, v145
	v_fma_f32 v145, -v157, v125, v145
	ds_read2_b32 v[156:157], v115 offset0:4 offset1:5
	s_waitcnt lgkmcnt(12)
	v_fma_f32 v145, -v158, v126, v145
	v_fma_f32 v145, -v159, v127, v145
	ds_read2_b32 v[158:159], v115 offset0:6 offset1:7
	s_waitcnt lgkmcnt(12)
	v_fma_f32 v145, -v160, v128, v145
	v_fma_f32 v145, -v161, v129, v145
	ds_read2_b32 v[160:161], v115 offset0:8 offset1:9
	s_waitcnt lgkmcnt(12)
	v_fma_f32 v145, -v162, v130, v145
	v_fma_f32 v145, -v163, v131, v145
	ds_read2_b32 v[162:163], v115 offset0:10 offset1:11
	s_waitcnt lgkmcnt(12)
	v_fma_f32 v145, -v164, v132, v145
	v_fma_f32 v145, -v165, v133, v145
	ds_read2_b32 v[164:165], v115 offset0:12 offset1:13
	s_waitcnt lgkmcnt(12)
	v_fma_f32 v145, -v166, v134, v145
	v_fma_f32 v145, -v167, v135, v145
	ds_read2_b32 v[166:167], v115 offset0:14 offset1:15
	s_waitcnt lgkmcnt(12)
	v_fma_f32 v145, -v168, v136, v145
	v_fma_f32 v145, -v169, v137, v145
	ds_read2_b32 v[168:169], v115 offset0:16 offset1:17
	s_waitcnt lgkmcnt(12)
	v_fma_f32 v145, -v170, v138, v145
	v_fma_f32 v145, -v171, v139, v145
	ds_read2_b32 v[170:171], v115 offset0:18 offset1:19
	s_waitcnt lgkmcnt(12)
	v_fma_f32 v145, -v172, v140, v145
	v_fma_f32 v145, -v173, v141, v145
	ds_read2_b32 v[172:173], v115 offset0:20 offset1:21
	s_waitcnt lgkmcnt(12)
	v_fma_f32 v145, -v174, v142, v145
	v_fma_f32 v145, -v175, v143, v145
	ds_read2_b32 v[174:175], v115 offset0:22 offset1:23
	s_waitcnt lgkmcnt(12)
	v_fma_f32 v145, -v176, v144, v145
	ds_read2_b32 v[176:177], v115 offset0:24 offset1:25
	s_waitcnt lgkmcnt(12)
	v_fma_f32 v146, -v152, v120, v146
	v_fma_f32 v146, -v153, v121, v146
	v_add_u32_e32 v115, 260, v115
	ds_read2_b32 v[152:153], v115 offset0:0 offset1:1
	s_waitcnt lgkmcnt(12)
; __device__ void dn_pre_item(const Params& p, int L, int idx) {
;     ...
;   if (wid == 0) {
;     const int blk = lane >> 5, j = lane & 31;
;     const float* Ab = As + (blk * 32) * 65 + blk * 32;
;     float x[32];
; #pragma unroll
;     for (int c = 0; c < 32; ++c) {
;       float r = (c == j) ? 1.0f : 0.0f;
; #pragma unroll
;       for (int s = 0; s < c; ++s) r -= Ab[c * 65 + s] * x[s];
;       x[c] = r;
;     }
	v_fma_f32 v146, -v154, v122, v146
	v_fma_f32 v146, -v155, v123, v146
	ds_read2_b32 v[154:155], v115 offset0:2 offset1:3
	s_waitcnt lgkmcnt(12)
	v_fma_f32 v146, -v156, v124, v146
	v_fma_f32 v146, -v157, v125, v146
	ds_read2_b32 v[156:157], v115 offset0:4 offset1:5
	s_waitcnt lgkmcnt(12)
	v_fma_f32 v146, -v158, v126, v146
	v_fma_f32 v146, -v159, v127, v146
	ds_read2_b32 v[158:159], v115 offset0:6 offset1:7
	s_waitcnt lgkmcnt(12)
	v_fma_f32 v146, -v160, v128, v146
	v_fma_f32 v146, -v161, v129, v146
	ds_read2_b32 v[160:161], v115 offset0:8 offset1:9
	s_waitcnt lgkmcnt(12)
	v_fma_f32 v146, -v162, v130, v146
	v_fma_f32 v146, -v163, v131, v146
	ds_read2_b32 v[162:163], v115 offset0:10 offset1:11
	s_waitcnt lgkmcnt(12)
	v_fma_f32 v146, -v164, v132, v146
	v_fma_f32 v146, -v165, v133, v146
	ds_read2_b32 v[164:165], v115 offset0:12 offset1:13
	s_waitcnt lgkmcnt(12)
	v_fma_f32 v146, -v166, v134, v146
	v_fma_f32 v146, -v167, v135, v146
	ds_read2_b32 v[166:167], v115 offset0:14 offset1:15
	s_waitcnt lgkmcnt(12)
	v_fma_f32 v146, -v168, v136, v146
	v_fma_f32 v146, -v169, v137, v146
	ds_read2_b32 v[168:169], v115 offset0:16 offset1:17
	s_waitcnt lgkmcnt(12)
	v_fma_f32 v146, -v170, v138, v146
	v_fma_f32 v146, -v171, v139, v146
	ds_read2_b32 v[170:171], v115 offset0:18 offset1:19
	s_waitcnt lgkmcnt(12)
	v_fma_f32 v146, -v172, v140, v146
	v_fma_f32 v146, -v173, v141, v146
	ds_read2_b32 v[172:173], v115 offset0:20 offset1:21
	s_waitcnt lgkmcnt(12)
	v_fma_f32 v146, -v174, v142, v146
	v_fma_f32 v146, -v175, v143, v146
	ds_read2_b32 v[174:175], v115 offset0:22 offset1:23
	s_waitcnt lgkmcnt(12)
	v_fma_f32 v146, -v176, v144, v146
	v_fma_f32 v146, -v177, v145, v146
	ds_read2_b32 v[176:177], v115 offset0:24 offset1:25
	s_waitcnt lgkmcnt(12)
	v_fma_f32 v147, -v152, v120, v147
	v_fma_f32 v147, -v153, v121, v147
	ds_read2_b32 v[152:153], v115 offset0:26 offset1:27
	s_waitcnt lgkmcnt(12)
	v_fma_f32 v147, -v154, v122, v147
	v_fma_f32 v147, -v155, v123, v147
	v_add_u32_e32 v115, 260, v115
	ds_read2_b32 v[154:155], v115 offset0:0 offset1:1
	s_waitcnt lgkmcnt(12)
	v_fma_f32 v147, -v156, v124, v147
	v_fma_f32 v147, -v157, v125, v147
	ds_read2_b32 v[156:157], v115 offset0:2 offset1:3
	s_waitcnt lgkmcnt(12)
	v_fma_f32 v147, -v158, v126, v147
	v_fma_f32 v147, -v159, v127, v147
	ds_read2_b32 v[158:159], v115 offset0:4 offset1:5
	s_waitcnt lgkmcnt(12)
	v_fma_f32 v147, -v160, v128, v147
	v_fma_f32 v147, -v161, v129, v147
	ds_read2_b32 v[160:161], v115 offset0:6 offset1:7
	s_waitcnt lgkmcnt(12)
	v_fma_f32 v147, -v162, v130, v147
	v_fma_f32 v147, -v163, v131, v147
	ds_read2_b32 v[162:163], v115 offset0:8 offset1:9
	s_waitcnt lgkmcnt(12)
	v_fma_f32 v147, -v164, v132, v147
	v_fma_f32 v147, -v165, v133, v147
	ds_read2_b32 v[164:165], v115 offset0:10 offset1:11
	s_waitcnt lgkmcnt(12)
	v_fma_f32 v147, -v166, v134, v147
	v_fma_f32 v147, -v167, v135, v147
	ds_read2_b32 v[166:167], v115 offset0:12 offset1:13
	s_waitcnt lgkmcnt(12)
	v_fma_f32 v147, -v168, v136, v147
	v_fma_f32 v147, -v169, v137, v147
	ds_read2_b32 v[168:169], v115 offset0:14 offset1:15
	s_waitcnt lgkmcnt(12)
	v_fma_f32 v147, -v170, v138, v147
	v_fma_f32 v147, -v171, v139, v147
	ds_read2_b32 v[170:171], v115 offset0:16 offset1:17
	s_waitcnt lgkmcnt(12)
	v_fma_f32 v147, -v172, v140, v147
	v_fma_f32 v147, -v173, v141, v147
	ds_read2_b32 v[172:173], v115 offset0:18 offset1:19
	s_waitcnt lgkmcnt(12)
	v_fma_f32 v147, -v174, v142, v147
	v_fma_f32 v147, -v175, v143, v147
	ds_read2_b32 v[174:175], v115 offset0:20 offset1:21
	s_waitcnt lgkmcnt(12)
	v_fma_f32 v147, -v176, v144, v147
	v_fma_f32 v147, -v177, v145, v147
	ds_read2_b32 v[176:177], v115 offset0:22 offset1:23
	s_waitcnt lgkmcnt(12)
	v_fma_f32 v147, -v152, v146, v147
	ds_read2_b32 v[152:153], v115 offset0:24 offset1:25
	s_waitcnt lgkmcnt(12)
	v_fma_f32 v148, -v154, v120, v148
	v_fma_f32 v148, -v155, v121, v148
	ds_read2_b32 v[154:155], v115 offset0:26 offset1:27
	s_waitcnt lgkmcnt(12)
	v_fma_f32 v148, -v156, v122, v148
	v_fma_f32 v148, -v157, v123, v148
	v_add_u32_e32 v115, 260, v115
	ds_read2_b32 v[156:157], v115 offset0:0 offset1:1
	s_waitcnt lgkmcnt(12)
	v_fma_f32 v148, -v158, v124, v148
	v_fma_f32 v148, -v159, v125, v148
	ds_read2_b32 v[158:159], v115 offset0:2 offset1:3
	s_waitcnt lgkmcnt(12)
	v_fma_f32 v148, -v160, v126, v148
	v_fma_f32 v148, -v161, v127, v148
	ds_read2_b32 v[160:161], v115 offset0:4 offset1:5
	s_waitcnt lgkmcnt(12)
	v_fma_f32 v148, -v162, v128, v148
	v_fma_f32 v148, -v163, v129, v148
	ds_read2_b32 v[162:163], v115 offset0:6 offset1:7
	s_waitcnt lgkmcnt(12)
	v_fma_f32 v148, -v164, v130, v148
	v_fma_f32 v148, -v165, v131, v148
	ds_read2_b32 v[164:165], v115 offset0:8 offset1:9
	s_waitcnt lgkmcnt(12)
	v_fma_f32 v148, -v166, v132, v148
	v_fma_f32 v148, -v167, v133, v148
	ds_read2_b32 v[166:167], v115 offset0:10 offset1:11
	s_waitcnt lgkmcnt(12)
	v_fma_f32 v148, -v168, v134, v148
	v_fma_f32 v148, -v169, v135, v148
	ds_read2_b32 v[168:169], v115 offset0:12 offset1:13
	s_waitcnt lgkmcnt(12)
	v_fma_f32 v148, -v170, v136, v148
	v_fma_f32 v148, -v171, v137, v148
	ds_read2_b32 v[170:171], v115 offset0:14 offset1:15
	s_waitcnt lgkmcnt(12)
	v_fma_f32 v148, -v172, v138, v148
	v_fma_f32 v148, -v173, v139, v148
	ds_read2_b32 v[172:173], v115 offset0:16 offset1:17
	s_waitcnt lgkmcnt(12)
	v_fma_f32 v148, -v174, v140, v148
	v_fma_f32 v148, -v175, v141, v148
	ds_read2_b32 v[174:175], v115 offset0:18 offset1:19
	s_waitcnt lgkmcnt(12)
	v_fma_f32 v148, -v176, v142, v148
	v_fma_f32 v148, -v177, v143, v148
	ds_read2_b32 v[176:177], v115 offset0:20 offset1:21
	s_waitcnt lgkmcnt(12)
	v_fma_f32 v148, -v152, v144, v148
	v_fma_f32 v148, -v153, v145, v148
	ds_read2_b32 v[152:153], v115 offset0:22 offset1:23
	s_waitcnt lgkmcnt(12)
; __device__ void dn_pre_item(const Params& p, int L, int idx) {
;     ...
;   if (wid == 0) {
;     const int blk = lane >> 5, j = lane & 31;
;     const float* Ab = As + (blk * 32) * 65 + blk * 32;
;     float x[32];
; #pragma unroll
;     for (int c = 0; c < 32; ++c) {
;       float r = (c == j) ? 1.0f : 0.0f;
; #pragma unroll
;       for (int s = 0; s < c; ++s) r -= Ab[c * 65 + s] * x[s];
;       x[c] = r;
;     }
	v_fma_f32 v148, -v154, v146, v148
	v_fma_f32 v148, -v155, v147, v148
	ds_read2_b32 v[154:155], v115 offset0:24 offset1:25
	s_waitcnt lgkmcnt(12)
	v_fma_f32 v149, -v156, v120, v149
	v_fma_f32 v149, -v157, v121, v149
	ds_read2_b32 v[156:157], v115 offset0:26 offset1:27
	s_waitcnt lgkmcnt(12)
	v_fma_f32 v149, -v158, v122, v149
	v_fma_f32 v149, -v159, v123, v149
	ds_read2_b32 v[158:159], v115 offset0:28 offset1:29
	s_waitcnt lgkmcnt(12)
	v_fma_f32 v149, -v160, v124, v149
	v_fma_f32 v149, -v161, v125, v149
	v_add_u32_e32 v115, 260, v115
	ds_read2_b32 v[160:161], v115 offset0:0 offset1:1
	s_waitcnt lgkmcnt(12)
	v_fma_f32 v149, -v162, v126, v149
	v_fma_f32 v149, -v163, v127, v149
	ds_read2_b32 v[162:163], v115 offset0:2 offset1:3
	s_waitcnt lgkmcnt(12)
	v_fma_f32 v149, -v164, v128, v149
	v_fma_f32 v149, -v165, v129, v149
	ds_read2_b32 v[164:165], v115 offset0:4 offset1:5
	s_waitcnt lgkmcnt(12)
	v_fma_f32 v149, -v166, v130, v149
	v_fma_f32 v149, -v167, v131, v149
	ds_read2_b32 v[166:167], v115 offset0:6 offset1:7
	s_waitcnt lgkmcnt(12)
	v_fma_f32 v149, -v168, v132, v149
	v_fma_f32 v149, -v169, v133, v149
	ds_read2_b32 v[168:169], v115 offset0:8 offset1:9
	s_waitcnt lgkmcnt(12)
	v_fma_f32 v149, -v170, v134, v149
	v_fma_f32 v149, -v171, v135, v149
	ds_read2_b32 v[170:171], v115 offset0:10 offset1:11
	s_waitcnt lgkmcnt(12)
	v_fma_f32 v149, -v172, v136, v149
	v_fma_f32 v149, -v173, v137, v149
	ds_read2_b32 v[172:173], v115 offset0:12 offset1:13
	s_waitcnt lgkmcnt(12)
	v_fma_f32 v149, -v174, v138, v149
	v_fma_f32 v149, -v175, v139, v149
	ds_read2_b32 v[174:175], v115 offset0:14 offset1:15
	s_waitcnt lgkmcnt(12)
	v_fma_f32 v149, -v176, v140, v149
	v_fma_f32 v149, -v177, v141, v149
	ds_read2_b32 v[176:177], v115 offset0:16 offset1:17
	s_waitcnt lgkmcnt(12)
	v_fma_f32 v149, -v152, v142, v149
	v_fma_f32 v149, -v153, v143, v149
	ds_read2_b32 v[152:153], v115 offset0:18 offset1:19
	s_waitcnt lgkmcnt(12)
	v_fma_f32 v149, -v154, v144, v149
	v_fma_f32 v149, -v155, v145, v149
	ds_read2_b32 v[154:155], v115 offset0:20 offset1:21
	s_waitcnt lgkmcnt(12)
	v_fma_f32 v149, -v156, v146, v149
	v_fma_f32 v149, -v157, v147, v149
	ds_read2_b32 v[156:157], v115 offset0:22 offset1:23
	s_waitcnt lgkmcnt(12)
	v_fma_f32 v149, -v158, v148, v149
	ds_read2_b32 v[158:159], v115 offset0:24 offset1:25
	s_waitcnt lgkmcnt(12)
	v_fma_f32 v150, -v160, v120, v150
	v_fma_f32 v150, -v161, v121, v150
	ds_read2_b32 v[160:161], v115 offset0:26 offset1:27
	s_waitcnt lgkmcnt(12)
	v_fma_f32 v150, -v162, v122, v150
	v_fma_f32 v150, -v163, v123, v150
	ds_read2_b32 v[162:163], v115 offset0:28 offset1:29
	s_waitcnt lgkmcnt(12)
	v_fma_f32 v150, -v164, v124, v150
	v_fma_f32 v150, -v165, v125, v150
	v_add_u32_e32 v115, 260, v115
	ds_read2_b32 v[164:165], v115 offset0:0 offset1:1
	s_waitcnt lgkmcnt(12)
	v_fma_f32 v150, -v166, v126, v150
	v_fma_f32 v150, -v167, v127, v150
	ds_read2_b32 v[166:167], v115 offset0:2 offset1:3
	s_waitcnt lgkmcnt(12)
	v_fma_f32 v150, -v168, v128, v150
	v_fma_f32 v150, -v169, v129, v150
	ds_read2_b32 v[168:169], v115 offset0:4 offset1:5
	s_waitcnt lgkmcnt(12)
	v_fma_f32 v150, -v170, v130, v150
	v_fma_f32 v150, -v171, v131, v150
	ds_read2_b32 v[170:171], v115 offset0:6 offset1:7
	s_waitcnt lgkmcnt(12)
	v_fma_f32 v150, -v172, v132, v150
	v_fma_f32 v150, -v173, v133, v150
	ds_read2_b32 v[172:173], v115 offset0:8 offset1:9
	s_waitcnt lgkmcnt(12)
	v_fma_f32 v150, -v174, v134, v150
	v_fma_f32 v150, -v175, v135, v150
	ds_read2_b32 v[174:175], v115 offset0:10 offset1:11
	s_waitcnt lgkmcnt(12)
	v_fma_f32 v150, -v176, v136, v150
	v_fma_f32 v150, -v177, v137, v150
	ds_read2_b32 v[176:177], v115 offset0:12 offset1:13
	s_waitcnt lgkmcnt(12)
; __device__ void dn_pre_item(const Params& p, int L, int idx) {
;     ...
; #pragma unroll
;     for (int c = 0; c < 32; ++c) {
;       float r = (c == j) ? 1.0f : 0.0f;
; #pragma unroll
;       for (int s = 0; s < c; ++s) r -= Ab[c * 65 + s] * x[s];
;       x[c] = r;
;     }
; #pragma unroll
;     for (int c = 0; c < 32; ++c) Tf[(blk * 32 + c) * 65 + blk * 32 + j] = x[c];
	v_fma_f32 v150, -v152, v138, v150
	v_fma_f32 v150, -v153, v139, v150
	ds_read2_b32 v[152:153], v115 offset0:14 offset1:15
	s_waitcnt lgkmcnt(12)
	v_fma_f32 v150, -v154, v140, v150
	v_fma_f32 v150, -v155, v141, v150
	ds_read2_b32 v[154:155], v115 offset0:16 offset1:17
	s_waitcnt lgkmcnt(12)
	v_fma_f32 v150, -v156, v142, v150
	v_fma_f32 v150, -v157, v143, v150
	ds_read2_b32 v[156:157], v115 offset0:18 offset1:19
	s_waitcnt lgkmcnt(12)
	v_fma_f32 v150, -v158, v144, v150
	v_fma_f32 v150, -v159, v145, v150
	ds_read2_b32 v[158:159], v115 offset0:20 offset1:21
	s_waitcnt lgkmcnt(12)
	v_fma_f32 v150, -v160, v146, v150
	v_fma_f32 v150, -v161, v147, v150
	ds_read2_b32 v[160:161], v115 offset0:22 offset1:23
	s_waitcnt lgkmcnt(12)
	v_fma_f32 v150, -v162, v148, v150
	v_fma_f32 v150, -v163, v149, v150
	ds_read2_b32 v[162:163], v115 offset0:24 offset1:25
	s_waitcnt lgkmcnt(12)
	v_fma_f32 v151, -v164, v120, v151
	v_fma_f32 v151, -v165, v121, v151
	ds_read2_b32 v[164:165], v115 offset0:26 offset1:27
	s_waitcnt lgkmcnt(12)
	v_fma_f32 v151, -v166, v122, v151
	v_fma_f32 v151, -v167, v123, v151
	ds_read2_b32 v[166:167], v115 offset0:28 offset1:29
	s_waitcnt lgkmcnt(12)
	v_fma_f32 v151, -v168, v124, v151
	v_fma_f32 v151, -v169, v125, v151
	ds_read2_b32 v[168:169], v115 offset0:30 offset1:31
	s_waitcnt lgkmcnt(12)
	v_fma_f32 v151, -v170, v126, v151
	v_fma_f32 v151, -v171, v127, v151
	s_waitcnt lgkmcnt(11)
	v_fma_f32 v151, -v172, v128, v151
	v_fma_f32 v151, -v173, v129, v151
	s_waitcnt lgkmcnt(10)
	v_fma_f32 v151, -v174, v130, v151
	v_fma_f32 v151, -v175, v131, v151
	s_waitcnt lgkmcnt(9)
	v_fma_f32 v151, -v176, v132, v151
	v_fma_f32 v151, -v177, v133, v151
	s_waitcnt lgkmcnt(8)
	v_fma_f32 v151, -v152, v134, v151
	v_fma_f32 v151, -v153, v135, v151
	s_waitcnt lgkmcnt(7)
	v_fma_f32 v151, -v154, v136, v151
	v_fma_f32 v151, -v155, v137, v151
	s_waitcnt lgkmcnt(6)
	v_fma_f32 v151, -v156, v138, v151
	v_fma_f32 v151, -v157, v139, v151
	s_waitcnt lgkmcnt(5)
	v_fma_f32 v151, -v158, v140, v151
	v_fma_f32 v151, -v159, v141, v151
	s_waitcnt lgkmcnt(4)
	v_fma_f32 v151, -v160, v142, v151
	v_fma_f32 v151, -v161, v143, v151
	s_waitcnt lgkmcnt(3)
	v_fma_f32 v151, -v162, v144, v151
	v_fma_f32 v151, -v163, v145, v151
	s_waitcnt lgkmcnt(2)
	v_fma_f32 v151, -v164, v146, v151
	v_fma_f32 v151, -v165, v147, v151
	s_waitcnt lgkmcnt(1)
	v_fma_f32 v151, -v166, v148, v151
	v_fma_f32 v151, -v167, v149, v151
	s_waitcnt lgkmcnt(0)
	v_fma_f32 v151, -v168, v150, v151
	ds_write_b32 v116, v120 offset:17408
	ds_write_b32 v116, v121 offset:17668
	ds_write_b32 v116, v122 offset:17928
	ds_write_b32 v116, v123 offset:18188
	ds_write_b32 v116, v124 offset:18448
	ds_write_b32 v116, v125 offset:18708
	ds_write_b32 v116, v126 offset:18968
	ds_write_b32 v116, v127 offset:19228
	ds_write_b32 v116, v128 offset:19488
	ds_write_b32 v116, v129 offset:19748
	ds_write_b32 v116, v130 offset:20008
	ds_write_b32 v116, v131 offset:20268
	ds_write_b32 v116, v132 offset:20528
	ds_write_b32 v116, v133 offset:20788
	ds_write_b32 v116, v134 offset:21048
	ds_write_b32 v116, v135 offset:21308
	ds_write_b32 v116, v136 offset:21568
	ds_write_b32 v116, v137 offset:21828
	ds_write_b32 v116, v138 offset:22088
	ds_write_b32 v116, v139 offset:22348
	ds_write_b32 v116, v140 offset:22608
	ds_write_b32 v116, v141 offset:22868
	ds_write_b32 v116, v142 offset:23128
	ds_write_b32 v116, v143 offset:23388
	ds_write_b32 v116, v144 offset:23648
	ds_write_b32 v116, v145 offset:23908
	ds_write_b32 v116, v146 offset:24168
	ds_write_b32 v116, v147 offset:24428
	ds_write_b32 v116, v148 offset:24688
	ds_write_b32 v116, v149 offset:24948
	ds_write_b32 v116, v150 offset:25208
	ds_write_b32 v116, v151 offset:25468
